# EpiUp fast path: GELU polynomial/exponent argument on packed f32 ops (same operations, two elements per instruction)
# speedup vs baseline: 1.0124x; 1.0071x over previous
;     __device__ __forceinline__ void operator()(const f32x4 (&acc)[2][2][4][2], const Unit& u, int wr, int wc, int fr, int fq) const {
;     ...
;         const bool samp = (u.pm == 64);
; #pragma unroll
;         for (int ai = 0; ai < 2; ++ai) {
;             const int rowb = u.pm * 256 + ai * 128 + wr * 64;
;             const int blk = 4 * u.pm + 2 * ai + wr;
;             float rs[4];
; #pragma unroll
;             for (int m = 0; m < 4; ++m) rs[m] = rsqrtf(SS[rowb + 16 * m + fr] * (1.0f / D) + EPS);
; #pragma unroll
;             for (int n = 0; n < 2; ++n) {
;                 f32x4 cg[4];
; #pragma unroll
;                 for (int bj = 0; bj < 2; ++bj) {
;                     const int oc = (bj ? FF : 0) + 128 * u.pn + 32 * wc + 8 * fq + 4 * n;
;                     const int cgc = 256 * u.pn + 128 * bj + 32 * wc + 8 * fq + 4 * n;
;                     const f32x4 cw0 = *(const f32x4*)(convw + oc), cw1 = *(const f32x4*)(convw + FF2 + oc), cw2 = *(const f32x4*)(convw + 2 * FF2 + oc), cb = *(const f32x4*)(convb + oc);
;                     f32x4 v[4];
; #pragma unroll
;                     for (int m = 0; m < 4; ++m) v[m] = acc[ai][bj][m][n] * rs[m];
.Lfe_begin:
	v_readlane_b32 s13, v236, 19
	s_lshl_b32 s77, s88, 8
	s_lshl_b32 s89, s12, 7
	s_lshl_b32 s75, s88, 2
	s_add_i32 s75, s75, s73
	s_add_i32 s77, s77, s13
	v_add_u32_e32 v246, s77, v153
	v_add_u32_e32 v247, s13, v153
	v_lshlrev_b32_e32 v247, 2, v247
	v_add_u32_e32 v247, 0x22000, v247
	ds_read2_b32 v[238:239], v247 offset0:0 offset1:16
	ds_read2_b32 v[240:241], v247 offset0:32 offset1:48
	ds_read2_b32 v[242:243], v247 offset0:128 offset1:144
	ds_read2_b32 v[244:245], v247 offset0:160 offset1:176
	v_lshlrev_b32_e32 v249, 2, v215
	v_add_u32_e32 v249, 0x21000, v249
	v_add_u32_e32 v248, s89, v215
	v_lshlrev_b32_e32 v237, 2, v248
	v_add_u32_e32 v250, 0x2c00, v237
	ds_read_b128 v[170:173], v249
	ds_read_b128 v[174:177], v249 offset:16
	ds_read_b128 v[178:181], v249 offset:512
	ds_read_b128 v[182:185], v249 offset:528
	ds_read_b128 v[186:189], v249 offset:1024
	ds_read_b128 v[190:193], v249 offset:1040
	ds_read_b128 v[194:197], v249 offset:1536
	ds_read_b128 v[198:201], v249 offset:1552
	v_mul_u32_u24_e32 v151, 0x1600, v246
	v_lshl_add_u32 v151, v248, 1, v151
	v_mov_b32_e32 v219, s64
	v_mov_b32_e32 v220, 0
	v_mov_b32_e32 v221, 0
	v_mov_b32_e32 v222, 0
	v_mov_b32_e32 v223, 0
	v_mov_b32_e32 v224, 0
	v_mov_b32_e32 v225, 0
	v_mov_b32_e32 v226, 0
	v_mov_b32_e32 v227, 0
	v_mov_b32_e32 v228, 0
	v_mov_b32_e32 v229, 0
	v_mov_b32_e32 v230, 0
	v_mov_b32_e32 v231, 0
	v_mov_b32_e32 v232, 0
	v_mov_b32_e32 v233, 0
	v_mov_b32_e32 v234, 0
	v_mov_b32_e32 v235, 0
	s_mul_i32 s56, s75, 0xb000
	s_lshl_b32 s57, s12, 10
	s_add_i32 s56, s56, s57
	v_mul_i32_i24_e32 v150, 0x5800, v216
	v_lshl_add_u32 v150, v215, 2, v150
	v_add_u32_e32 v150, s56, v150
	s_waitcnt lgkmcnt(8)
	v_fmamk_f32 v238, v238, 0x3a800000, v218
	v_fmamk_f32 v239, v239, 0x3a800000, v218
	v_fmamk_f32 v240, v240, 0x3a800000, v218
	v_fmamk_f32 v241, v241, 0x3a800000, v218
	v_fmamk_f32 v242, v242, 0x3a800000, v218
	v_fmamk_f32 v243, v243, 0x3a800000, v218
	v_fmamk_f32 v244, v244, 0x3a800000, v218
	v_fmamk_f32 v245, v245, 0x3a800000, v218
	v_rsq_f32_e32 v238, v238
	v_rsq_f32_e32 v239, v239
	v_rsq_f32_e32 v240, v240
	v_rsq_f32_e32 v241, v241
	v_rsq_f32_e32 v242, v242
	v_rsq_f32_e32 v243, v243
	v_rsq_f32_e32 v244, v244
	v_rsq_f32_e32 v245, v245
	ds_read_b128 v[202:205], v249 offset:2048
	ds_read_b128 v[206:209], v249 offset:2064
	ds_read_b128 v[210:213], v249 offset:2560
	ds_read_b128 v[128:131], v249 offset:2576
	ds_read_b128 v[132:135], v249 offset:3072
	ds_read_b128 v[136:139], v249 offset:3088
	ds_read_b128 v[140:143], v249 offset:3584
	ds_read_b128 v[144:147], v249 offset:3600
	v_pk_mul_f32 v[124:125], v[124:125], v[238:239] op_sel_hi:[1,0]
	v_pk_mul_f32 v[126:127], v[126:127], v[238:239] op_sel_hi:[1,0]
	v_pk_mul_f32 v[92:93], v[92:93], v[238:239] op_sel_hi:[1,0]
	v_pk_mul_f32 v[94:95], v[94:95], v[238:239] op_sel_hi:[1,0]
	v_pk_mul_f32 v[108:109], v[108:109], v[238:239] op_sel_hi:[1,0]
	v_pk_mul_f32 v[110:111], v[110:111], v[238:239] op_sel_hi:[1,0]
	v_pk_mul_f32 v[76:77], v[76:77], v[238:239] op_sel_hi:[1,0]
	v_pk_mul_f32 v[78:79], v[78:79], v[238:239] op_sel_hi:[1,0]
	v_pk_mul_f32 v[120:121], v[120:121], v[238:239] op_sel:[0,1] op_sel_hi:[1,1]
	v_pk_mul_f32 v[122:123], v[122:123], v[238:239] op_sel:[0,1] op_sel_hi:[1,1]
	v_pk_mul_f32 v[88:89], v[88:89], v[238:239] op_sel:[0,1] op_sel_hi:[1,1]
	v_pk_mul_f32 v[90:91], v[90:91], v[238:239] op_sel:[0,1] op_sel_hi:[1,1]
	v_pk_mul_f32 v[104:105], v[104:105], v[238:239] op_sel:[0,1] op_sel_hi:[1,1]
	v_pk_mul_f32 v[106:107], v[106:107], v[238:239] op_sel:[0,1] op_sel_hi:[1,1]
	v_pk_mul_f32 v[72:73], v[72:73], v[238:239] op_sel:[0,1] op_sel_hi:[1,1]
	v_pk_mul_f32 v[74:75], v[74:75], v[238:239] op_sel:[0,1] op_sel_hi:[1,1]
	v_pk_mul_f32 v[116:117], v[116:117], v[240:241] op_sel_hi:[1,0]
	v_pk_mul_f32 v[118:119], v[118:119], v[240:241] op_sel_hi:[1,0]
	v_pk_mul_f32 v[84:85], v[84:85], v[240:241] op_sel_hi:[1,0]
	v_pk_mul_f32 v[86:87], v[86:87], v[240:241] op_sel_hi:[1,0]
	v_pk_mul_f32 v[100:101], v[100:101], v[240:241] op_sel_hi:[1,0]
	v_pk_mul_f32 v[102:103], v[102:103], v[240:241] op_sel_hi:[1,0]
	v_pk_mul_f32 v[68:69], v[68:69], v[240:241] op_sel_hi:[1,0]
	v_pk_mul_f32 v[70:71], v[70:71], v[240:241] op_sel_hi:[1,0]
	v_pk_mul_f32 v[112:113], v[112:113], v[240:241] op_sel:[0,1] op_sel_hi:[1,1]
	v_pk_mul_f32 v[114:115], v[114:115], v[240:241] op_sel:[0,1] op_sel_hi:[1,1]
	v_pk_mul_f32 v[80:81], v[80:81], v[240:241] op_sel:[0,1] op_sel_hi:[1,1]
	v_pk_mul_f32 v[82:83], v[82:83], v[240:241] op_sel:[0,1] op_sel_hi:[1,1]
	v_pk_mul_f32 v[96:97], v[96:97], v[240:241] op_sel:[0,1] op_sel_hi:[1,1]
	v_pk_mul_f32 v[98:99], v[98:99], v[240:241] op_sel:[0,1] op_sel_hi:[1,1]
	v_pk_mul_f32 v[64:65], v[64:65], v[240:241] op_sel:[0,1] op_sel_hi:[1,1]
	v_pk_mul_f32 v[66:67], v[66:67], v[240:241] op_sel:[0,1] op_sel_hi:[1,1]
	v_pk_mul_f32 v[60:61], v[60:61], v[242:243] op_sel_hi:[1,0]
	v_pk_mul_f32 v[62:63], v[62:63], v[242:243] op_sel_hi:[1,0]
	v_pk_mul_f32 v[28:29], v[28:29], v[242:243] op_sel_hi:[1,0]
	v_pk_mul_f32 v[30:31], v[30:31], v[242:243] op_sel_hi:[1,0]
	v_pk_mul_f32 v[44:45], v[44:45], v[242:243] op_sel_hi:[1,0]
	v_pk_mul_f32 v[46:47], v[46:47], v[242:243] op_sel_hi:[1,0]
	v_pk_mul_f32 v[12:13], v[12:13], v[242:243] op_sel_hi:[1,0]
	v_pk_mul_f32 v[14:15], v[14:15], v[242:243] op_sel_hi:[1,0]
	v_pk_mul_f32 v[52:53], v[52:53], v[242:243] op_sel:[0,1] op_sel_hi:[1,1]
	v_pk_mul_f32 v[54:55], v[54:55], v[242:243] op_sel:[0,1] op_sel_hi:[1,1]
	v_pk_mul_f32 v[20:21], v[20:21], v[242:243] op_sel:[0,1] op_sel_hi:[1,1]
	v_pk_mul_f32 v[22:23], v[22:23], v[242:243] op_sel:[0,1] op_sel_hi:[1,1]
	v_pk_mul_f32 v[36:37], v[36:37], v[242:243] op_sel:[0,1] op_sel_hi:[1,1]
	v_pk_mul_f32 v[38:39], v[38:39], v[242:243] op_sel:[0,1] op_sel_hi:[1,1]
	v_pk_mul_f32 v[4:5], v[4:5], v[242:243] op_sel:[0,1] op_sel_hi:[1,1]
	v_pk_mul_f32 v[6:7], v[6:7], v[242:243] op_sel:[0,1] op_sel_hi:[1,1]
	v_pk_mul_f32 v[48:49], v[48:49], v[244:245] op_sel_hi:[1,0]
	v_pk_mul_f32 v[50:51], v[50:51], v[244:245] op_sel_hi:[1,0]
	v_pk_mul_f32 v[16:17], v[16:17], v[244:245] op_sel_hi:[1,0]
	v_pk_mul_f32 v[18:19], v[18:19], v[244:245] op_sel_hi:[1,0]
	v_pk_mul_f32 v[32:33], v[32:33], v[244:245] op_sel_hi:[1,0]
	v_pk_mul_f32 v[34:35], v[34:35], v[244:245] op_sel_hi:[1,0]
	v_pk_mul_f32 v[0:1], v[0:1], v[244:245] op_sel_hi:[1,0]
	v_pk_mul_f32 v[2:3], v[2:3], v[244:245] op_sel_hi:[1,0]
	v_pk_mul_f32 v[56:57], v[56:57], v[244:245] op_sel:[0,1] op_sel_hi:[1,1]
	v_pk_mul_f32 v[58:59], v[58:59], v[244:245] op_sel:[0,1] op_sel_hi:[1,1]
	v_pk_mul_f32 v[24:25], v[24:25], v[244:245] op_sel:[0,1] op_sel_hi:[1,1]
	v_pk_mul_f32 v[26:27], v[26:27], v[244:245] op_sel:[0,1] op_sel_hi:[1,1]
	v_pk_mul_f32 v[40:41], v[40:41], v[244:245] op_sel:[0,1] op_sel_hi:[1,1]
	v_pk_mul_f32 v[42:43], v[42:43], v[244:245] op_sel:[0,1] op_sel_hi:[1,1]
	v_pk_mul_f32 v[8:9], v[8:9], v[244:245] op_sel:[0,1] op_sel_hi:[1,1]
	v_pk_mul_f32 v[10:11], v[10:11], v[244:245] op_sel:[0,1] op_sel_hi:[1,1]
	s_waitcnt lgkmcnt(0)
; __device__ __forceinline__ f32x2 gelu_pk(f32x2 v) {
;     const f32x2 av = __builtin_elementwise_abs(v), d = av * 0.2316418882f + 1.0f;
;     __device__ __forceinline__ void operator()(const f32x4 (&acc)[2][2][4][2], const Unit& u, int wr, int wc, int fr, int fq) const {
;     ...
; #pragma unroll
;                     for (int m = 0; m < 4; ++m) {
;                         f32x4 cv;
;                         if (!samp) {
;                             const f32x4 prev = m ? v[m - 1] : hv;
; #pragma unroll
;                             for (int e = 0; e < 4; ++e) {
;                                 const int vi = __float_as_int(v[m][e]), pi = __float_as_int(prev[e]);
;                                 const int o1 = __builtin_amdgcn_mov_dpp(pi, 0x121, 0xf, 0xf, false);
;                                 const int o2 = __builtin_amdgcn_mov_dpp(pi, 0x122, 0xf, 0xf, false);
;                                 const float p1 = __int_as_float(__builtin_amdgcn_update_dpp(o1, vi, 0x111, 0xf, 0xf, false));
;                                 const float p2 = __int_as_float(__builtin_amdgcn_update_dpp(o2, vi, 0x112, 0xf, 0xf, false));
;                                 cv[e] = cb[e] + cw0[e] * p2 + cw1[e] * p1 + cw2[e] * v[m][e];
;                             }
;                         } else {
;                             const int ns = rowb + 16 * m + fr - MP;
;                             f32x4 s0 = (f32x4){0.f, 0.f, 0.f, 0.f}, s1 = s0;
;                             if (ns < NS) {
;                                 s0 = *(const f32x4*)(state + (size_t)(ns * 2 + 0) * FF2 + oc); s1 = *(const f32x4*)(state + (size_t)(ns * 2 + 1) * FF2 + oc);
;                                 *(f32x4*)(ncs + (size_t)(ns * 2 + 0) * FF2 + oc) = s1; *(f32x4*)(ncs + (size_t)(ns * 2 + 1) * FF2 + oc) = v[m];
;                             }
;                             cv = cb + cw0 * s0 + cw1 * s1 + cw2 * v[m];
;                         }
;                         if (bj == 0) cg[m] = gelu4(cv);
;                         else {
;                             const f32x4 r = cg[m] * cv;
;                             v2u w; w.x = cvt_pk_bf16(r[0], r[1]); w.y = cvt_pk_bf16(r[2], r[3]);
;                             *(v2u*)(ACT + (size_t)(rowb + 16 * m + fr) * FF + 128 * u.pn + 32 * wc + 8 * fq + 4 * n) = w;
;                         }
	s_mov_b32 s56, 0x3f07dc22
	v_mov_b32_dpp v220, v116 quad_perm:[0,1,2,3] row_mask:0xf bank_mask:0x8
	v_mov_b32_dpp v221, v117 quad_perm:[0,1,2,3] row_mask:0xf bank_mask:0x8
	v_mov_b32_dpp v222, v118 quad_perm:[0,1,2,3] row_mask:0xf bank_mask:0x8
	v_mov_b32_dpp v223, v119 quad_perm:[0,1,2,3] row_mask:0xf bank_mask:0x8
	v_pk_fma_f32 v[254:255], v[202:203], v[112:113], v[132:133]
	v_pk_fma_f32 v[148:149], v[204:205], v[114:115], v[134:135]
	v_fmac_f32_dpp v254, v112, v186 row_shr:1 row_mask:0xf bank_mask:0xf
	v_fmac_f32_dpp v255, v113, v187 row_shr:1 row_mask:0xf bank_mask:0xf
	v_fmac_f32_dpp v148, v114, v188 row_shr:1 row_mask:0xf bank_mask:0xf
	v_fmac_f32_dpp v149, v115, v189 row_shr:1 row_mask:0xf bank_mask:0xf
	v_fmac_f32_dpp v254, v112, v170 row_shr:2 row_mask:0xf bank_mask:0xf
	v_fmac_f32_dpp v255, v113, v171 row_shr:2 row_mask:0xf bank_mask:0xf
	v_fmac_f32_dpp v148, v114, v172 row_shr:2 row_mask:0xf bank_mask:0xf
	v_fmac_f32_dpp v149, v115, v173 row_shr:2 row_mask:0xf bank_mask:0xf
	v_fmac_f32_dpp v254, v220, v186 row_ror:1 row_mask:0xf bank_mask:0x1
	v_fmac_f32_dpp v255, v221, v187 row_ror:1 row_mask:0xf bank_mask:0x1
	v_fmac_f32_dpp v148, v222, v188 row_ror:1 row_mask:0xf bank_mask:0x1
	v_fmac_f32_dpp v149, v223, v189 row_ror:1 row_mask:0xf bank_mask:0x1
	v_fmac_f32_dpp v254, v220, v170 row_ror:2 row_mask:0xf bank_mask:0x1
	v_fmac_f32_dpp v255, v221, v171 row_ror:2 row_mask:0xf bank_mask:0x1
	v_fmac_f32_dpp v148, v222, v172 row_ror:2 row_mask:0xf bank_mask:0x1
	v_fmac_f32_dpp v149, v223, v173 row_ror:2 row_mask:0xf bank_mask:0x1
	v_fma_f32 v246, |v254|, s38, 1.0
	v_fma_f32 v247, |v255|, s38, 1.0
	v_fma_f32 v248, |v148|, s38, 1.0
	v_fma_f32 v249, |v149|, s38, 1.0
	v_pk_mul_f32 v[250:251], v[254:255], v[254:255]
	v_pk_mul_f32 v[252:253], v[148:149], v[148:149]
	v_rcp_f32_e32 v246, v246
	v_rcp_f32_e32 v247, v247
	v_rcp_f32_e32 v248, v248
	v_rcp_f32_e32 v249, v249
	v_pk_mul_f32 v[250:251], v[250:251], s[72:73] op_sel_hi:[1,0]
	v_pk_mul_f32 v[252:253], v[252:253], s[72:73] op_sel_hi:[1,0]
	v_exp_f32_e32 v250, v250
	v_exp_f32_e32 v251, v251
	v_exp_f32_e32 v252, v252
	v_exp_f32_e32 v253, v253
	v_pk_fma_f32 v[238:239], v[246:247], s[56:57], v[218:219] op_sel:[0,0,1] op_sel_hi:[1,0,1]
	v_pk_fma_f32 v[240:241], v[248:249], s[56:57], v[218:219] op_sel:[0,0,1] op_sel_hi:[1,0,1]
	v_pk_fma_f32 v[238:239], v[246:247], v[238:239], s[66:67] op_sel_hi:[1,1,0]
	v_pk_fma_f32 v[240:241], v[248:249], v[240:241], s[66:67] op_sel_hi:[1,1,0]
	v_pk_fma_f32 v[238:239], v[246:247], v[238:239], s[68:69] op_sel_hi:[1,1,0]
	v_pk_fma_f32 v[240:241], v[248:249], v[240:241], s[68:69] op_sel_hi:[1,1,0]
	v_pk_fma_f32 v[238:239], v[246:247], v[238:239], s[70:71] op_sel_hi:[1,1,0]
	v_pk_fma_f32 v[240:241], v[248:249], v[240:241], s[70:71] op_sel_hi:[1,1,0]
	v_pk_mul_f32 v[238:239], v[246:247], v[238:239]
	v_pk_mul_f32 v[240:241], v[248:249], v[240:241]
	v_pk_mul_f32 v[238:239], v[250:251], v[238:239]
	v_pk_mul_f32 v[240:241], v[252:253], v[240:241]
	v_max_f32_e32 v246, 0, v254
	v_max_f32_e32 v247, 0, v255
	v_max_f32_e32 v248, 0, v148
	v_max_f32_e32 v249, 0, v149
	v_fma_f32 v238, -|v254|, v238, v246
	v_fma_f32 v239, -|v255|, v239, v247
	v_fma_f32 v240, -|v148|, v240, v248
	v_fma_f32 v241, -|v149|, v241, v249
	v_mov_b32_dpp v220, v100 quad_perm:[0,1,2,3] row_mask:0xf bank_mask:0x8
	v_mov_b32_dpp v221, v101 quad_perm:[0,1,2,3] row_mask:0xf bank_mask:0x8
	v_mov_b32_dpp v222, v102 quad_perm:[0,1,2,3] row_mask:0xf bank_mask:0x8
	v_mov_b32_dpp v223, v103 quad_perm:[0,1,2,3] row_mask:0xf bank_mask:0x8
	v_pk_fma_f32 v[254:255], v[210:211], v[96:97], v[140:141]
	v_pk_fma_f32 v[148:149], v[212:213], v[98:99], v[142:143]
	v_fmac_f32_dpp v254, v96, v194 row_shr:1 row_mask:0xf bank_mask:0xf
	v_fmac_f32_dpp v255, v97, v195 row_shr:1 row_mask:0xf bank_mask:0xf
	v_fmac_f32_dpp v148, v98, v196 row_shr:1 row_mask:0xf bank_mask:0xf
	v_fmac_f32_dpp v149, v99, v197 row_shr:1 row_mask:0xf bank_mask:0xf
	v_fmac_f32_dpp v254, v96, v178 row_shr:2 row_mask:0xf bank_mask:0xf
	v_fmac_f32_dpp v255, v97, v179 row_shr:2 row_mask:0xf bank_mask:0xf
	v_fmac_f32_dpp v148, v98, v180 row_shr:2 row_mask:0xf bank_mask:0xf
	v_fmac_f32_dpp v149, v99, v181 row_shr:2 row_mask:0xf bank_mask:0xf
	v_fmac_f32_dpp v254, v220, v194 row_ror:1 row_mask:0xf bank_mask:0x1
	v_fmac_f32_dpp v255, v221, v195 row_ror:1 row_mask:0xf bank_mask:0x1
	v_fmac_f32_dpp v148, v222, v196 row_ror:1 row_mask:0xf bank_mask:0x1
	v_fmac_f32_dpp v149, v223, v197 row_ror:1 row_mask:0xf bank_mask:0x1
	v_fmac_f32_dpp v254, v220, v178 row_ror:2 row_mask:0xf bank_mask:0x1
	v_fmac_f32_dpp v255, v221, v179 row_ror:2 row_mask:0xf bank_mask:0x1
	v_fmac_f32_dpp v148, v222, v180 row_ror:2 row_mask:0xf bank_mask:0x1
	v_fmac_f32_dpp v149, v223, v181 row_ror:2 row_mask:0xf bank_mask:0x1
	v_pk_mul_f32 v[254:255], v[238:239], v[254:255]
	v_pk_mul_f32 v[148:149], v[240:241], v[148:149]
	v_cvt_pk_bf16_f32 v242, v254, v255
	v_cvt_pk_bf16_f32 v243, v148, v149
	v_mov_b32_dpp v220, v84 quad_perm:[0,1,2,3] row_mask:0xf bank_mask:0x8
	v_mov_b32_dpp v221, v85 quad_perm:[0,1,2,3] row_mask:0xf bank_mask:0x8
	v_mov_b32_dpp v222, v86 quad_perm:[0,1,2,3] row_mask:0xf bank_mask:0x8
	v_mov_b32_dpp v223, v87 quad_perm:[0,1,2,3] row_mask:0xf bank_mask:0x8
	v_pk_fma_f32 v[254:255], v[206:207], v[80:81], v[136:137]
	v_pk_fma_f32 v[148:149], v[208:209], v[82:83], v[138:139]
	v_fmac_f32_dpp v254, v80, v190 row_shr:1 row_mask:0xf bank_mask:0xf
	v_fmac_f32_dpp v255, v81, v191 row_shr:1 row_mask:0xf bank_mask:0xf
	v_fmac_f32_dpp v148, v82, v192 row_shr:1 row_mask:0xf bank_mask:0xf
	v_fmac_f32_dpp v149, v83, v193 row_shr:1 row_mask:0xf bank_mask:0xf
; __device__ __forceinline__ f32x2 gelu_pk(f32x2 v) {
;     const f32x2 av = __builtin_elementwise_abs(v), d = av * 0.2316418882f + 1.0f;
;     __device__ __forceinline__ void operator()(const f32x4 (&acc)[2][2][4][2], const Unit& u, int wr, int wc, int fr, int fq) const {
;     ...
; #pragma unroll
;                     for (int m = 0; m < 4; ++m) {
;                         f32x4 cv;
;                         if (!samp) {
;                             const f32x4 prev = m ? v[m - 1] : hv;
; #pragma unroll
;                             for (int e = 0; e < 4; ++e) {
;                                 const int vi = __float_as_int(v[m][e]), pi = __float_as_int(prev[e]);
;                                 const int o1 = __builtin_amdgcn_mov_dpp(pi, 0x121, 0xf, 0xf, false);
;                                 const int o2 = __builtin_amdgcn_mov_dpp(pi, 0x122, 0xf, 0xf, false);
;                                 const float p1 = __int_as_float(__builtin_amdgcn_update_dpp(o1, vi, 0x111, 0xf, 0xf, false));
;                                 const float p2 = __int_as_float(__builtin_amdgcn_update_dpp(o2, vi, 0x112, 0xf, 0xf, false));
;                                 cv[e] = cb[e] + cw0[e] * p2 + cw1[e] * p1 + cw2[e] * v[m][e];
;                             }
;                         } else {
;                             const int ns = rowb + 16 * m + fr - MP;
;                             f32x4 s0 = (f32x4){0.f, 0.f, 0.f, 0.f}, s1 = s0;
;                             if (ns < NS) {
;                                 s0 = *(const f32x4*)(state + (size_t)(ns * 2 + 0) * FF2 + oc); s1 = *(const f32x4*)(state + (size_t)(ns * 2 + 1) * FF2 + oc);
;                                 *(f32x4*)(ncs + (size_t)(ns * 2 + 0) * FF2 + oc) = s1; *(f32x4*)(ncs + (size_t)(ns * 2 + 1) * FF2 + oc) = v[m];
;                             }
;                             cv = cb + cw0 * s0 + cw1 * s1 + cw2 * v[m];
;                         }
;                         if (bj == 0) cg[m] = gelu4(cv);
;                         else {
;                             const f32x4 r = cg[m] * cv;
;                             v2u w; w.x = cvt_pk_bf16(r[0], r[1]); w.y = cvt_pk_bf16(r[2], r[3]);
;                             *(v2u*)(ACT + (size_t)(rowb + 16 * m + fr) * FF + 128 * u.pn + 32 * wc + 8 * fq + 4 * n) = w;
;                         }
	v_fmac_f32_dpp v254, v80, v174 row_shr:2 row_mask:0xf bank_mask:0xf
	v_fmac_f32_dpp v255, v81, v175 row_shr:2 row_mask:0xf bank_mask:0xf
	v_fmac_f32_dpp v148, v82, v176 row_shr:2 row_mask:0xf bank_mask:0xf
	v_fmac_f32_dpp v149, v83, v177 row_shr:2 row_mask:0xf bank_mask:0xf
	v_fmac_f32_dpp v254, v220, v190 row_ror:1 row_mask:0xf bank_mask:0x1
	v_fmac_f32_dpp v255, v221, v191 row_ror:1 row_mask:0xf bank_mask:0x1
	v_fmac_f32_dpp v148, v222, v192 row_ror:1 row_mask:0xf bank_mask:0x1
	v_fmac_f32_dpp v149, v223, v193 row_ror:1 row_mask:0xf bank_mask:0x1
	v_fmac_f32_dpp v254, v220, v174 row_ror:2 row_mask:0xf bank_mask:0x1
	v_fmac_f32_dpp v255, v221, v175 row_ror:2 row_mask:0xf bank_mask:0x1
	v_fmac_f32_dpp v148, v222, v176 row_ror:2 row_mask:0xf bank_mask:0x1
	v_fmac_f32_dpp v149, v223, v177 row_ror:2 row_mask:0xf bank_mask:0x1
	v_fma_f32 v246, |v254|, s38, 1.0
	v_fma_f32 v247, |v255|, s38, 1.0
	v_fma_f32 v248, |v148|, s38, 1.0
	v_fma_f32 v249, |v149|, s38, 1.0
	v_pk_mul_f32 v[250:251], v[254:255], v[254:255]
	v_pk_mul_f32 v[252:253], v[148:149], v[148:149]
	v_rcp_f32_e32 v246, v246
	v_rcp_f32_e32 v247, v247
	v_rcp_f32_e32 v248, v248
	v_rcp_f32_e32 v249, v249
	v_pk_mul_f32 v[250:251], v[250:251], s[72:73] op_sel_hi:[1,0]
	v_pk_mul_f32 v[252:253], v[252:253], s[72:73] op_sel_hi:[1,0]
	v_exp_f32_e32 v250, v250
	v_exp_f32_e32 v251, v251
	v_exp_f32_e32 v252, v252
	v_exp_f32_e32 v253, v253
	v_pk_fma_f32 v[238:239], v[246:247], s[56:57], v[218:219] op_sel:[0,0,1] op_sel_hi:[1,0,1]
	v_pk_fma_f32 v[240:241], v[248:249], s[56:57], v[218:219] op_sel:[0,0,1] op_sel_hi:[1,0,1]
	v_pk_fma_f32 v[238:239], v[246:247], v[238:239], s[66:67] op_sel_hi:[1,1,0]
	v_pk_fma_f32 v[240:241], v[248:249], v[240:241], s[66:67] op_sel_hi:[1,1,0]
	v_pk_fma_f32 v[238:239], v[246:247], v[238:239], s[68:69] op_sel_hi:[1,1,0]
	v_pk_fma_f32 v[240:241], v[248:249], v[240:241], s[68:69] op_sel_hi:[1,1,0]
	v_pk_fma_f32 v[238:239], v[246:247], v[238:239], s[70:71] op_sel_hi:[1,1,0]
	v_pk_fma_f32 v[240:241], v[248:249], v[240:241], s[70:71] op_sel_hi:[1,1,0]
	v_pk_mul_f32 v[238:239], v[246:247], v[238:239]
	v_pk_mul_f32 v[240:241], v[248:249], v[240:241]
	v_pk_mul_f32 v[238:239], v[250:251], v[238:239]
	v_pk_mul_f32 v[240:241], v[252:253], v[240:241]
	v_max_f32_e32 v246, 0, v254
	v_max_f32_e32 v247, 0, v255
	v_max_f32_e32 v248, 0, v148
	v_max_f32_e32 v249, 0, v149
	v_fma_f32 v238, -|v254|, v238, v246
	v_fma_f32 v239, -|v255|, v239, v247
	v_fma_f32 v240, -|v148|, v240, v248
	v_fma_f32 v241, -|v149|, v241, v249
	v_mov_b32_dpp v220, v68 quad_perm:[0,1,2,3] row_mask:0xf bank_mask:0x8
	v_mov_b32_dpp v221, v69 quad_perm:[0,1,2,3] row_mask:0xf bank_mask:0x8
	v_mov_b32_dpp v222, v70 quad_perm:[0,1,2,3] row_mask:0xf bank_mask:0x8
	v_mov_b32_dpp v223, v71 quad_perm:[0,1,2,3] row_mask:0xf bank_mask:0x8
	v_pk_fma_f32 v[254:255], v[128:129], v[64:65], v[144:145]
	v_pk_fma_f32 v[148:149], v[130:131], v[66:67], v[146:147]
	v_fmac_f32_dpp v254, v64, v198 row_shr:1 row_mask:0xf bank_mask:0xf
	v_fmac_f32_dpp v255, v65, v199 row_shr:1 row_mask:0xf bank_mask:0xf
	v_fmac_f32_dpp v148, v66, v200 row_shr:1 row_mask:0xf bank_mask:0xf
	v_fmac_f32_dpp v149, v67, v201 row_shr:1 row_mask:0xf bank_mask:0xf
	v_fmac_f32_dpp v254, v64, v182 row_shr:2 row_mask:0xf bank_mask:0xf
	v_fmac_f32_dpp v255, v65, v183 row_shr:2 row_mask:0xf bank_mask:0xf
	v_fmac_f32_dpp v148, v66, v184 row_shr:2 row_mask:0xf bank_mask:0xf
	v_fmac_f32_dpp v149, v67, v185 row_shr:2 row_mask:0xf bank_mask:0xf
	v_fmac_f32_dpp v254, v220, v198 row_ror:1 row_mask:0xf bank_mask:0x1
	v_fmac_f32_dpp v255, v221, v199 row_ror:1 row_mask:0xf bank_mask:0x1
	v_fmac_f32_dpp v148, v222, v200 row_ror:1 row_mask:0xf bank_mask:0x1
	v_fmac_f32_dpp v149, v223, v201 row_ror:1 row_mask:0xf bank_mask:0x1
	v_fmac_f32_dpp v254, v220, v182 row_ror:2 row_mask:0xf bank_mask:0x1
	v_fmac_f32_dpp v255, v221, v183 row_ror:2 row_mask:0xf bank_mask:0x1
	v_fmac_f32_dpp v148, v222, v184 row_ror:2 row_mask:0xf bank_mask:0x1
	v_fmac_f32_dpp v149, v223, v185 row_ror:2 row_mask:0xf bank_mask:0x1
	v_pk_mul_f32 v[254:255], v[238:239], v[254:255]
	v_pk_mul_f32 v[148:149], v[240:241], v[148:149]
	v_cvt_pk_bf16_f32 v244, v254, v255
	v_cvt_pk_bf16_f32 v245, v148, v149
	s_add_u32 s56, s46, 0x42000
	s_addc_u32 s57, s47, 0
	global_store_dwordx4 v151, v[242:245], s[56:57]
	v_mov_b32_e32 v112, 0
	v_mov_b32_e32 v113, 0
	v_mov_b32_e32 v114, 0
	v_mov_b32_e32 v115, 0
	s_mov_b32 s56, 0x3f07dc22
	v_mov_b32_dpp v112, v120 quad_perm:[0,1,2,3] row_mask:0xf bank_mask:0x8
	v_mov_b32_dpp v113, v121 quad_perm:[0,1,2,3] row_mask:0xf bank_mask:0x8
	v_mov_b32_dpp v114, v122 quad_perm:[0,1,2,3] row_mask:0xf bank_mask:0x8
	v_mov_b32_dpp v115, v123 quad_perm:[0,1,2,3] row_mask:0xf bank_mask:0x8
	v_pk_fma_f32 v[254:255], v[202:203], v[116:117], v[132:133]
	v_pk_fma_f32 v[148:149], v[204:205], v[118:119], v[134:135]
	v_fmac_f32_dpp v254, v116, v186 row_shr:1 row_mask:0xf bank_mask:0xf
	v_fmac_f32_dpp v255, v117, v187 row_shr:1 row_mask:0xf bank_mask:0xf
	v_fmac_f32_dpp v148, v118, v188 row_shr:1 row_mask:0xf bank_mask:0xf
	v_fmac_f32_dpp v149, v119, v189 row_shr:1 row_mask:0xf bank_mask:0xf
	v_fmac_f32_dpp v254, v116, v170 row_shr:2 row_mask:0xf bank_mask:0xf
	v_fmac_f32_dpp v255, v117, v171 row_shr:2 row_mask:0xf bank_mask:0xf
	v_fmac_f32_dpp v148, v118, v172 row_shr:2 row_mask:0xf bank_mask:0xf
	v_fmac_f32_dpp v149, v119, v173 row_shr:2 row_mask:0xf bank_mask:0xf
	v_fmac_f32_dpp v254, v112, v186 row_ror:1 row_mask:0xf bank_mask:0x1
	v_fmac_f32_dpp v255, v113, v187 row_ror:1 row_mask:0xf bank_mask:0x1
	v_fmac_f32_dpp v148, v114, v188 row_ror:1 row_mask:0xf bank_mask:0x1
	v_fmac_f32_dpp v149, v115, v189 row_ror:1 row_mask:0xf bank_mask:0x1
; __device__ __forceinline__ f32x2 gelu_pk(f32x2 v) {
;     const f32x2 av = __builtin_elementwise_abs(v), d = av * 0.2316418882f + 1.0f;
;     __device__ __forceinline__ void operator()(const f32x4 (&acc)[2][2][4][2], const Unit& u, int wr, int wc, int fr, int fq) const {
;     ...
; #pragma unroll
;                     for (int m = 0; m < 4; ++m) {
;                         f32x4 cv;
;                         if (!samp) {
;                             const f32x4 prev = m ? v[m - 1] : hv;
; #pragma unroll
;                             for (int e = 0; e < 4; ++e) {
;                                 const int vi = __float_as_int(v[m][e]), pi = __float_as_int(prev[e]);
;                                 const int o1 = __builtin_amdgcn_mov_dpp(pi, 0x121, 0xf, 0xf, false);
;                                 const int o2 = __builtin_amdgcn_mov_dpp(pi, 0x122, 0xf, 0xf, false);
;                                 const float p1 = __int_as_float(__builtin_amdgcn_update_dpp(o1, vi, 0x111, 0xf, 0xf, false));
;                                 const float p2 = __int_as_float(__builtin_amdgcn_update_dpp(o2, vi, 0x112, 0xf, 0xf, false));
;                                 cv[e] = cb[e] + cw0[e] * p2 + cw1[e] * p1 + cw2[e] * v[m][e];
;                             }
;                         } else {
;                             const int ns = rowb + 16 * m + fr - MP;
;                             f32x4 s0 = (f32x4){0.f, 0.f, 0.f, 0.f}, s1 = s0;
;                             if (ns < NS) {
;                                 s0 = *(const f32x4*)(state + (size_t)(ns * 2 + 0) * FF2 + oc); s1 = *(const f32x4*)(state + (size_t)(ns * 2 + 1) * FF2 + oc);
;                                 *(f32x4*)(ncs + (size_t)(ns * 2 + 0) * FF2 + oc) = s1; *(f32x4*)(ncs + (size_t)(ns * 2 + 1) * FF2 + oc) = v[m];
;                             }
;                             cv = cb + cw0 * s0 + cw1 * s1 + cw2 * v[m];
;                         }
;                         if (bj == 0) cg[m] = gelu4(cv);
;                         else {
;                             const f32x4 r = cg[m] * cv;
;                             v2u w; w.x = cvt_pk_bf16(r[0], r[1]); w.y = cvt_pk_bf16(r[2], r[3]);
;                             *(v2u*)(ACT + (size_t)(rowb + 16 * m + fr) * FF + 128 * u.pn + 32 * wc + 8 * fq + 4 * n) = w;
;                         }
	v_fmac_f32_dpp v254, v112, v170 row_ror:2 row_mask:0xf bank_mask:0x1
	v_fmac_f32_dpp v255, v113, v171 row_ror:2 row_mask:0xf bank_mask:0x1
	v_fmac_f32_dpp v148, v114, v172 row_ror:2 row_mask:0xf bank_mask:0x1
	v_fmac_f32_dpp v149, v115, v173 row_ror:2 row_mask:0xf bank_mask:0x1
	v_fma_f32 v246, |v254|, s38, 1.0
	v_fma_f32 v247, |v255|, s38, 1.0
	v_fma_f32 v248, |v148|, s38, 1.0
	v_fma_f32 v249, |v149|, s38, 1.0
	v_pk_mul_f32 v[250:251], v[254:255], v[254:255]
	v_pk_mul_f32 v[252:253], v[148:149], v[148:149]
	v_rcp_f32_e32 v246, v246
	v_rcp_f32_e32 v247, v247
	v_rcp_f32_e32 v248, v248
	v_rcp_f32_e32 v249, v249
	v_pk_mul_f32 v[250:251], v[250:251], s[72:73] op_sel_hi:[1,0]
	v_pk_mul_f32 v[252:253], v[252:253], s[72:73] op_sel_hi:[1,0]
	v_exp_f32_e32 v250, v250
	v_exp_f32_e32 v251, v251
	v_exp_f32_e32 v252, v252
	v_exp_f32_e32 v253, v253
	v_pk_fma_f32 v[238:239], v[246:247], s[56:57], v[218:219] op_sel:[0,0,1] op_sel_hi:[1,0,1]
	v_pk_fma_f32 v[240:241], v[248:249], s[56:57], v[218:219] op_sel:[0,0,1] op_sel_hi:[1,0,1]
	v_pk_fma_f32 v[238:239], v[246:247], v[238:239], s[66:67] op_sel_hi:[1,1,0]
	v_pk_fma_f32 v[240:241], v[248:249], v[240:241], s[66:67] op_sel_hi:[1,1,0]
	v_pk_fma_f32 v[238:239], v[246:247], v[238:239], s[68:69] op_sel_hi:[1,1,0]
	v_pk_fma_f32 v[240:241], v[248:249], v[240:241], s[68:69] op_sel_hi:[1,1,0]
	v_pk_fma_f32 v[238:239], v[246:247], v[238:239], s[70:71] op_sel_hi:[1,1,0]
	v_pk_fma_f32 v[240:241], v[248:249], v[240:241], s[70:71] op_sel_hi:[1,1,0]
	v_pk_mul_f32 v[238:239], v[246:247], v[238:239]
	v_pk_mul_f32 v[240:241], v[248:249], v[240:241]
	v_pk_mul_f32 v[238:239], v[250:251], v[238:239]
	v_pk_mul_f32 v[240:241], v[252:253], v[240:241]
	v_max_f32_e32 v246, 0, v254
	v_max_f32_e32 v247, 0, v255
	v_max_f32_e32 v248, 0, v148
	v_max_f32_e32 v249, 0, v149
	v_fma_f32 v238, -|v254|, v238, v246
	v_fma_f32 v239, -|v255|, v239, v247
	v_fma_f32 v240, -|v148|, v240, v248
	v_fma_f32 v241, -|v149|, v241, v249
	v_mov_b32_dpp v112, v104 quad_perm:[0,1,2,3] row_mask:0xf bank_mask:0x8
	v_mov_b32_dpp v113, v105 quad_perm:[0,1,2,3] row_mask:0xf bank_mask:0x8
	v_mov_b32_dpp v114, v106 quad_perm:[0,1,2,3] row_mask:0xf bank_mask:0x8
	v_mov_b32_dpp v115, v107 quad_perm:[0,1,2,3] row_mask:0xf bank_mask:0x8
	v_pk_fma_f32 v[254:255], v[210:211], v[100:101], v[140:141]
	v_pk_fma_f32 v[148:149], v[212:213], v[102:103], v[142:143]
	v_fmac_f32_dpp v254, v100, v194 row_shr:1 row_mask:0xf bank_mask:0xf
	v_fmac_f32_dpp v255, v101, v195 row_shr:1 row_mask:0xf bank_mask:0xf
	v_fmac_f32_dpp v148, v102, v196 row_shr:1 row_mask:0xf bank_mask:0xf
	v_fmac_f32_dpp v149, v103, v197 row_shr:1 row_mask:0xf bank_mask:0xf
	v_fmac_f32_dpp v254, v100, v178 row_shr:2 row_mask:0xf bank_mask:0xf
	v_fmac_f32_dpp v255, v101, v179 row_shr:2 row_mask:0xf bank_mask:0xf
	v_fmac_f32_dpp v148, v102, v180 row_shr:2 row_mask:0xf bank_mask:0xf
	v_fmac_f32_dpp v149, v103, v181 row_shr:2 row_mask:0xf bank_mask:0xf
	v_fmac_f32_dpp v254, v112, v194 row_ror:1 row_mask:0xf bank_mask:0x1
	v_fmac_f32_dpp v255, v113, v195 row_ror:1 row_mask:0xf bank_mask:0x1
	v_fmac_f32_dpp v148, v114, v196 row_ror:1 row_mask:0xf bank_mask:0x1
	v_fmac_f32_dpp v149, v115, v197 row_ror:1 row_mask:0xf bank_mask:0x1
	v_fmac_f32_dpp v254, v112, v178 row_ror:2 row_mask:0xf bank_mask:0x1
	v_fmac_f32_dpp v255, v113, v179 row_ror:2 row_mask:0xf bank_mask:0x1
	v_fmac_f32_dpp v148, v114, v180 row_ror:2 row_mask:0xf bank_mask:0x1
	v_fmac_f32_dpp v149, v115, v181 row_ror:2 row_mask:0xf bank_mask:0x1
	v_pk_mul_f32 v[254:255], v[238:239], v[254:255]
	v_pk_mul_f32 v[148:149], v[240:241], v[148:149]
	v_cvt_pk_bf16_f32 v242, v254, v255
	v_cvt_pk_bf16_f32 v243, v148, v149
	v_mov_b32_dpp v112, v88 quad_perm:[0,1,2,3] row_mask:0xf bank_mask:0x8
	v_mov_b32_dpp v113, v89 quad_perm:[0,1,2,3] row_mask:0xf bank_mask:0x8
	v_mov_b32_dpp v114, v90 quad_perm:[0,1,2,3] row_mask:0xf bank_mask:0x8
	v_mov_b32_dpp v115, v91 quad_perm:[0,1,2,3] row_mask:0xf bank_mask:0x8
	v_pk_fma_f32 v[254:255], v[206:207], v[84:85], v[136:137]
	v_pk_fma_f32 v[148:149], v[208:209], v[86:87], v[138:139]
	v_fmac_f32_dpp v254, v84, v190 row_shr:1 row_mask:0xf bank_mask:0xf
	v_fmac_f32_dpp v255, v85, v191 row_shr:1 row_mask:0xf bank_mask:0xf
	v_fmac_f32_dpp v148, v86, v192 row_shr:1 row_mask:0xf bank_mask:0xf
	v_fmac_f32_dpp v149, v87, v193 row_shr:1 row_mask:0xf bank_mask:0xf
	v_fmac_f32_dpp v254, v84, v174 row_shr:2 row_mask:0xf bank_mask:0xf
	v_fmac_f32_dpp v255, v85, v175 row_shr:2 row_mask:0xf bank_mask:0xf
	v_fmac_f32_dpp v148, v86, v176 row_shr:2 row_mask:0xf bank_mask:0xf
	v_fmac_f32_dpp v149, v87, v177 row_shr:2 row_mask:0xf bank_mask:0xf
	v_fmac_f32_dpp v254, v112, v190 row_ror:1 row_mask:0xf bank_mask:0x1
	v_fmac_f32_dpp v255, v113, v191 row_ror:1 row_mask:0xf bank_mask:0x1
	v_fmac_f32_dpp v148, v114, v192 row_ror:1 row_mask:0xf bank_mask:0x1
	v_fmac_f32_dpp v149, v115, v193 row_ror:1 row_mask:0xf bank_mask:0x1
	v_fmac_f32_dpp v254, v112, v174 row_ror:2 row_mask:0xf bank_mask:0x1
	v_fmac_f32_dpp v255, v113, v175 row_ror:2 row_mask:0xf bank_mask:0x1
	v_fmac_f32_dpp v148, v114, v176 row_ror:2 row_mask:0xf bank_mask:0x1
	v_fmac_f32_dpp v149, v115, v177 row_ror:2 row_mask:0xf bank_mask:0x1
	v_fma_f32 v246, |v254|, s38, 1.0
	v_fma_f32 v247, |v255|, s38, 1.0
	v_fma_f32 v248, |v148|, s38, 1.0
	v_fma_f32 v249, |v149|, s38, 1.0
	v_pk_mul_f32 v[250:251], v[254:255], v[254:255]
	v_pk_mul_f32 v[252:253], v[148:149], v[148:149]
	v_rcp_f32_e32 v246, v246
	v_rcp_f32_e32 v247, v247
	v_rcp_f32_e32 v248, v248
	v_rcp_f32_e32 v249, v249
	v_pk_mul_f32 v[250:251], v[250:251], s[72:73] op_sel_hi:[1,0]
	v_pk_mul_f32 v[252:253], v[252:253], s[72:73] op_sel_hi:[1,0]
;     __device__ __forceinline__ void operator()(const f32x4 (&acc)[2][2][4][2], const Unit& u, int wr, int wc, int fr, int fq) const {
;     ...
;                     if (!samp) {
;                         if ((blk & 31) != 0 && fr >= 14) hv = *(const f32x4*)(HALO + (size_t)(2 * blk + fr - 14) * FF2 + cgc);
;     ...
; #pragma unroll
;                     for (int m = 0; m < 4; ++m) {
;                         f32x4 cv;
;                         if (!samp) {
;                             const f32x4 prev = m ? v[m - 1] : hv;
; #pragma unroll
;                             for (int e = 0; e < 4; ++e) {
;                                 const int vi = __float_as_int(v[m][e]), pi = __float_as_int(prev[e]);
;                                 const int o1 = __builtin_amdgcn_mov_dpp(pi, 0x121, 0xf, 0xf, false);
;                                 const int o2 = __builtin_amdgcn_mov_dpp(pi, 0x122, 0xf, 0xf, false);
;                                 const float p1 = __int_as_float(__builtin_amdgcn_update_dpp(o1, vi, 0x111, 0xf, 0xf, false));
;                                 const float p2 = __int_as_float(__builtin_amdgcn_update_dpp(o2, vi, 0x112, 0xf, 0xf, false));
;                                 cv[e] = cb[e] + cw0[e] * p2 + cw1[e] * p1 + cw2[e] * v[m][e];
;                             }
;                         } else {
;                             const int ns = rowb + 16 * m + fr - MP;
;                             f32x4 s0 = (f32x4){0.f, 0.f, 0.f, 0.f}, s1 = s0;
;                             if (ns < NS) {
;                                 s0 = *(const f32x4*)(state + (size_t)(ns * 2 + 0) * FF2 + oc); s1 = *(const f32x4*)(state + (size_t)(ns * 2 + 1) * FF2 + oc);
;                                 *(f32x4*)(ncs + (size_t)(ns * 2 + 0) * FF2 + oc) = s1; *(f32x4*)(ncs + (size_t)(ns * 2 + 1) * FF2 + oc) = v[m];
;                             }
;                             cv = cb + cw0 * s0 + cw1 * s1 + cw2 * v[m];
;                         }
;                         if (bj == 0) cg[m] = gelu4(cv);
;                         else {
;                             const f32x4 r = cg[m] * cv;
;                             v2u w; w.x = cvt_pk_bf16(r[0], r[1]); w.y = cvt_pk_bf16(r[2], r[3]);
;                             *(v2u*)(ACT + (size_t)(rowb + 16 * m + fr) * FF + 128 * u.pn + 32 * wc + 8 * fq + 4 * n) = w;
;                         }
	v_exp_f32_e32 v250, v250
	v_exp_f32_e32 v251, v251
	v_exp_f32_e32 v252, v252
	v_exp_f32_e32 v253, v253
	v_pk_fma_f32 v[238:239], v[246:247], s[56:57], v[218:219] op_sel:[0,0,1] op_sel_hi:[1,0,1]
	v_pk_fma_f32 v[240:241], v[248:249], s[56:57], v[218:219] op_sel:[0,0,1] op_sel_hi:[1,0,1]
	v_pk_fma_f32 v[238:239], v[246:247], v[238:239], s[66:67] op_sel_hi:[1,1,0]
	v_pk_fma_f32 v[240:241], v[248:249], v[240:241], s[66:67] op_sel_hi:[1,1,0]
	v_pk_fma_f32 v[238:239], v[246:247], v[238:239], s[68:69] op_sel_hi:[1,1,0]
	v_pk_fma_f32 v[240:241], v[248:249], v[240:241], s[68:69] op_sel_hi:[1,1,0]
	v_pk_fma_f32 v[238:239], v[246:247], v[238:239], s[70:71] op_sel_hi:[1,1,0]
	v_pk_fma_f32 v[240:241], v[248:249], v[240:241], s[70:71] op_sel_hi:[1,1,0]
	v_pk_mul_f32 v[238:239], v[246:247], v[238:239]
	v_pk_mul_f32 v[240:241], v[248:249], v[240:241]
	v_pk_mul_f32 v[238:239], v[250:251], v[238:239]
	v_pk_mul_f32 v[240:241], v[252:253], v[240:241]
	v_max_f32_e32 v246, 0, v254
	v_max_f32_e32 v247, 0, v255
	v_max_f32_e32 v248, 0, v148
	v_max_f32_e32 v249, 0, v149
	v_fma_f32 v238, -|v254|, v238, v246
	v_fma_f32 v239, -|v255|, v239, v247
	v_fma_f32 v240, -|v148|, v240, v248
	v_fma_f32 v241, -|v149|, v241, v249
	v_mov_b32_dpp v112, v72 quad_perm:[0,1,2,3] row_mask:0xf bank_mask:0x8
	v_mov_b32_dpp v113, v73 quad_perm:[0,1,2,3] row_mask:0xf bank_mask:0x8
	v_mov_b32_dpp v114, v74 quad_perm:[0,1,2,3] row_mask:0xf bank_mask:0x8
	v_mov_b32_dpp v115, v75 quad_perm:[0,1,2,3] row_mask:0xf bank_mask:0x8
	v_pk_fma_f32 v[254:255], v[128:129], v[68:69], v[144:145]
	v_pk_fma_f32 v[148:149], v[130:131], v[70:71], v[146:147]
	v_fmac_f32_dpp v254, v68, v198 row_shr:1 row_mask:0xf bank_mask:0xf
	v_fmac_f32_dpp v255, v69, v199 row_shr:1 row_mask:0xf bank_mask:0xf
	v_fmac_f32_dpp v148, v70, v200 row_shr:1 row_mask:0xf bank_mask:0xf
	v_fmac_f32_dpp v149, v71, v201 row_shr:1 row_mask:0xf bank_mask:0xf
	v_fmac_f32_dpp v254, v68, v182 row_shr:2 row_mask:0xf bank_mask:0xf
	v_fmac_f32_dpp v255, v69, v183 row_shr:2 row_mask:0xf bank_mask:0xf
	v_fmac_f32_dpp v148, v70, v184 row_shr:2 row_mask:0xf bank_mask:0xf
	v_fmac_f32_dpp v149, v71, v185 row_shr:2 row_mask:0xf bank_mask:0xf
	v_fmac_f32_dpp v254, v112, v198 row_ror:1 row_mask:0xf bank_mask:0x1
	v_fmac_f32_dpp v255, v113, v199 row_ror:1 row_mask:0xf bank_mask:0x1
	v_fmac_f32_dpp v148, v114, v200 row_ror:1 row_mask:0xf bank_mask:0x1
	v_fmac_f32_dpp v149, v115, v201 row_ror:1 row_mask:0xf bank_mask:0x1
	v_fmac_f32_dpp v254, v112, v182 row_ror:2 row_mask:0xf bank_mask:0x1
	v_fmac_f32_dpp v255, v113, v183 row_ror:2 row_mask:0xf bank_mask:0x1
	v_fmac_f32_dpp v148, v114, v184 row_ror:2 row_mask:0xf bank_mask:0x1
	v_fmac_f32_dpp v149, v115, v185 row_ror:2 row_mask:0xf bank_mask:0x1
	v_pk_mul_f32 v[254:255], v[238:239], v[254:255]
	v_pk_mul_f32 v[148:149], v[240:241], v[148:149]
	v_cvt_pk_bf16_f32 v244, v254, v255
	v_cvt_pk_bf16_f32 v245, v148, v149
	s_add_u32 s56, s46, 0x2c000
	s_addc_u32 s57, s47, 0
	global_store_dwordx4 v151, v[242:245], s[56:57]
	v_mov_b32_e32 v220, 0
	v_mov_b32_e32 v221, 0
	v_mov_b32_e32 v222, 0
	v_mov_b32_e32 v223, 0
	v_mov_b32_e32 v116, 0
	v_mov_b32_e32 v117, 0
	v_mov_b32_e32 v118, 0
	v_mov_b32_e32 v119, 0
	v_mov_b32_e32 v84, 0
	v_mov_b32_e32 v85, 0
	v_mov_b32_e32 v86, 0
	v_mov_b32_e32 v87, 0
	v_mov_b32_e32 v100, 0
	v_mov_b32_e32 v101, 0
	v_mov_b32_e32 v102, 0
	v_mov_b32_e32 v103, 0
	v_mov_b32_e32 v68, 0
	v_mov_b32_e32 v69, 0
	v_mov_b32_e32 v70, 0
	v_mov_b32_e32 v71, 0
	s_and_b32 s14, s75, 31
	s_cselect_b64 s[92:93], -1, 0
	v_add_u32_e32 v246, 0x16000, v150
	s_and_b64 vcc, exec, s[86:87]
	s_cbranch_vccnz .Lfe_h0a
	s_mov_b64 s[14:15], exec
	s_mov_b64 exec, s[10:11]
	global_load_dwordx4 v[116:119], v246, s[44:45]
	global_load_dwordx4 v[84:87], v246, s[44:45] offset:16
	global_load_dwordx4 v[100:103], v246, s[44:45] offset:512
	global_load_dwordx4 v[68:71], v246, s[44:45] offset:528
	s_mov_b64 exec, s[14:15]
	s_and_b64 vcc, exec, s[92:93]
	s_cbranch_vccz .Lfe_h0a
	s_mov_b64 s[14:15], exec
	s_mov_b64 exec, s[10:11]
	global_load_dwordx4 v[220:223], v150, s[44:45]
	global_load_dwordx4 v[224:227], v150, s[44:45] offset:16
	global_load_dwordx4 v[228:231], v150, s[44:45] offset:512
	global_load_dwordx4 v[232:235], v150, s[44:45] offset:528
	s_mov_b64 exec, s[14:15]
; __device__ __forceinline__ f32x2 gelu_pk(f32x2 v) {
;     const f32x2 av = __builtin_elementwise_abs(v), d = av * 0.2316418882f + 1.0f;
;     __device__ __forceinline__ void operator()(const f32x4 (&acc)[2][2][4][2], const Unit& u, int wr, int wc, int fr, int fq) const {
;     ...
; #pragma unroll
;                     for (int m = 0; m < 4; ++m) {
;                         f32x4 cv;
;                         if (!samp) {
;                             const f32x4 prev = m ? v[m - 1] : hv;
; #pragma unroll
;                             for (int e = 0; e < 4; ++e) {
;                                 const int vi = __float_as_int(v[m][e]), pi = __float_as_int(prev[e]);
;                                 const int o1 = __builtin_amdgcn_mov_dpp(pi, 0x121, 0xf, 0xf, false);
;                                 const int o2 = __builtin_amdgcn_mov_dpp(pi, 0x122, 0xf, 0xf, false);
;                                 const float p1 = __int_as_float(__builtin_amdgcn_update_dpp(o1, vi, 0x111, 0xf, 0xf, false));
;                                 const float p2 = __int_as_float(__builtin_amdgcn_update_dpp(o2, vi, 0x112, 0xf, 0xf, false));
;                                 cv[e] = cb[e] + cw0[e] * p2 + cw1[e] * p1 + cw2[e] * v[m][e];
;                             }
;                         } else {
;                             const int ns = rowb + 16 * m + fr - MP;
;                             f32x4 s0 = (f32x4){0.f, 0.f, 0.f, 0.f}, s1 = s0;
;                             if (ns < NS) {
;                                 s0 = *(const f32x4*)(state + (size_t)(ns * 2 + 0) * FF2 + oc); s1 = *(const f32x4*)(state + (size_t)(ns * 2 + 1) * FF2 + oc);
;                                 *(f32x4*)(ncs + (size_t)(ns * 2 + 0) * FF2 + oc) = s1; *(f32x4*)(ncs + (size_t)(ns * 2 + 1) * FF2 + oc) = v[m];
;                             }
;                             cv = cb + cw0 * s0 + cw1 * s1 + cw2 * v[m];
;                         }
;                         if (bj == 0) cg[m] = gelu4(cv);
;                         else {
;                             const f32x4 r = cg[m] * cv;
;                             v2u w; w.x = cvt_pk_bf16(r[0], r[1]); w.y = cvt_pk_bf16(r[2], r[3]);
;                             *(v2u*)(ACT + (size_t)(rowb + 16 * m + fr) * FF + 128 * u.pn + 32 * wc + 8 * fq + 4 * n) = w;
;                         }
.Lfe_h0a:
	s_mov_b32 s56, 0x3f07dc22
	v_mov_b32_dpp v112, v124 quad_perm:[0,1,2,3] row_mask:0xf bank_mask:0x8
	v_mov_b32_dpp v113, v125 quad_perm:[0,1,2,3] row_mask:0xf bank_mask:0x8
	v_mov_b32_dpp v114, v126 quad_perm:[0,1,2,3] row_mask:0xf bank_mask:0x8
	v_mov_b32_dpp v115, v127 quad_perm:[0,1,2,3] row_mask:0xf bank_mask:0x8
	v_pk_fma_f32 v[254:255], v[202:203], v[120:121], v[132:133]
	v_pk_fma_f32 v[148:149], v[204:205], v[122:123], v[134:135]
	v_fmac_f32_dpp v254, v120, v186 row_shr:1 row_mask:0xf bank_mask:0xf
	v_fmac_f32_dpp v255, v121, v187 row_shr:1 row_mask:0xf bank_mask:0xf
	v_fmac_f32_dpp v148, v122, v188 row_shr:1 row_mask:0xf bank_mask:0xf
	v_fmac_f32_dpp v149, v123, v189 row_shr:1 row_mask:0xf bank_mask:0xf
	v_fmac_f32_dpp v254, v120, v170 row_shr:2 row_mask:0xf bank_mask:0xf
	v_fmac_f32_dpp v255, v121, v171 row_shr:2 row_mask:0xf bank_mask:0xf
	v_fmac_f32_dpp v148, v122, v172 row_shr:2 row_mask:0xf bank_mask:0xf
	v_fmac_f32_dpp v149, v123, v173 row_shr:2 row_mask:0xf bank_mask:0xf
	v_fmac_f32_dpp v254, v112, v186 row_ror:1 row_mask:0xf bank_mask:0x1
	v_fmac_f32_dpp v255, v113, v187 row_ror:1 row_mask:0xf bank_mask:0x1
	v_fmac_f32_dpp v148, v114, v188 row_ror:1 row_mask:0xf bank_mask:0x1
	v_fmac_f32_dpp v149, v115, v189 row_ror:1 row_mask:0xf bank_mask:0x1
	v_fmac_f32_dpp v254, v112, v170 row_ror:2 row_mask:0xf bank_mask:0x1
	v_fmac_f32_dpp v255, v113, v171 row_ror:2 row_mask:0xf bank_mask:0x1
	v_fmac_f32_dpp v148, v114, v172 row_ror:2 row_mask:0xf bank_mask:0x1
	v_fmac_f32_dpp v149, v115, v173 row_ror:2 row_mask:0xf bank_mask:0x1
	v_fma_f32 v246, |v254|, s38, 1.0
	v_fma_f32 v247, |v255|, s38, 1.0
	v_fma_f32 v248, |v148|, s38, 1.0
	v_fma_f32 v249, |v149|, s38, 1.0
	v_pk_mul_f32 v[250:251], v[254:255], v[254:255]
	v_pk_mul_f32 v[252:253], v[148:149], v[148:149]
	v_rcp_f32_e32 v246, v246
	v_rcp_f32_e32 v247, v247
	v_rcp_f32_e32 v248, v248
	v_rcp_f32_e32 v249, v249
	v_pk_mul_f32 v[250:251], v[250:251], s[72:73] op_sel_hi:[1,0]
	v_pk_mul_f32 v[252:253], v[252:253], s[72:73] op_sel_hi:[1,0]
	v_exp_f32_e32 v250, v250
	v_exp_f32_e32 v251, v251
	v_exp_f32_e32 v252, v252
	v_exp_f32_e32 v253, v253
	v_pk_fma_f32 v[238:239], v[246:247], s[56:57], v[218:219] op_sel:[0,0,1] op_sel_hi:[1,0,1]
	v_pk_fma_f32 v[240:241], v[248:249], s[56:57], v[218:219] op_sel:[0,0,1] op_sel_hi:[1,0,1]
	v_pk_fma_f32 v[238:239], v[246:247], v[238:239], s[66:67] op_sel_hi:[1,1,0]
	v_pk_fma_f32 v[240:241], v[248:249], v[240:241], s[66:67] op_sel_hi:[1,1,0]
	v_pk_fma_f32 v[238:239], v[246:247], v[238:239], s[68:69] op_sel_hi:[1,1,0]
	v_pk_fma_f32 v[240:241], v[248:249], v[240:241], s[68:69] op_sel_hi:[1,1,0]
	v_pk_fma_f32 v[238:239], v[246:247], v[238:239], s[70:71] op_sel_hi:[1,1,0]
	v_pk_fma_f32 v[240:241], v[248:249], v[240:241], s[70:71] op_sel_hi:[1,1,0]
	v_pk_mul_f32 v[238:239], v[246:247], v[238:239]
	v_pk_mul_f32 v[240:241], v[248:249], v[240:241]
	v_pk_mul_f32 v[238:239], v[250:251], v[238:239]
	v_pk_mul_f32 v[240:241], v[252:253], v[240:241]
	v_max_f32_e32 v246, 0, v254
	v_max_f32_e32 v247, 0, v255
	v_max_f32_e32 v248, 0, v148
	v_max_f32_e32 v249, 0, v149
	v_fma_f32 v238, -|v254|, v238, v246
	v_fma_f32 v239, -|v255|, v239, v247
	v_fma_f32 v240, -|v148|, v240, v248
	v_fma_f32 v241, -|v149|, v241, v249
	v_mov_b32_dpp v112, v108 quad_perm:[0,1,2,3] row_mask:0xf bank_mask:0x8
	v_mov_b32_dpp v113, v109 quad_perm:[0,1,2,3] row_mask:0xf bank_mask:0x8
	v_mov_b32_dpp v114, v110 quad_perm:[0,1,2,3] row_mask:0xf bank_mask:0x8
	v_mov_b32_dpp v115, v111 quad_perm:[0,1,2,3] row_mask:0xf bank_mask:0x8
	v_pk_fma_f32 v[254:255], v[210:211], v[104:105], v[140:141]
	v_pk_fma_f32 v[148:149], v[212:213], v[106:107], v[142:143]
	v_fmac_f32_dpp v254, v104, v194 row_shr:1 row_mask:0xf bank_mask:0xf
	v_fmac_f32_dpp v255, v105, v195 row_shr:1 row_mask:0xf bank_mask:0xf
	v_fmac_f32_dpp v148, v106, v196 row_shr:1 row_mask:0xf bank_mask:0xf
	v_fmac_f32_dpp v149, v107, v197 row_shr:1 row_mask:0xf bank_mask:0xf
	v_fmac_f32_dpp v254, v104, v178 row_shr:2 row_mask:0xf bank_mask:0xf
	v_fmac_f32_dpp v255, v105, v179 row_shr:2 row_mask:0xf bank_mask:0xf
	v_fmac_f32_dpp v148, v106, v180 row_shr:2 row_mask:0xf bank_mask:0xf
	v_fmac_f32_dpp v149, v107, v181 row_shr:2 row_mask:0xf bank_mask:0xf
	v_fmac_f32_dpp v254, v112, v194 row_ror:1 row_mask:0xf bank_mask:0x1
	v_fmac_f32_dpp v255, v113, v195 row_ror:1 row_mask:0xf bank_mask:0x1
	v_fmac_f32_dpp v148, v114, v196 row_ror:1 row_mask:0xf bank_mask:0x1
	v_fmac_f32_dpp v149, v115, v197 row_ror:1 row_mask:0xf bank_mask:0x1
	v_fmac_f32_dpp v254, v112, v178 row_ror:2 row_mask:0xf bank_mask:0x1
	v_fmac_f32_dpp v255, v113, v179 row_ror:2 row_mask:0xf bank_mask:0x1
	v_fmac_f32_dpp v148, v114, v180 row_ror:2 row_mask:0xf bank_mask:0x1
	v_fmac_f32_dpp v149, v115, v181 row_ror:2 row_mask:0xf bank_mask:0x1
	v_pk_mul_f32 v[254:255], v[238:239], v[254:255]
	v_pk_mul_f32 v[148:149], v[240:241], v[148:149]
	v_cvt_pk_bf16_f32 v242, v254, v255
	v_cvt_pk_bf16_f32 v243, v148, v149
	v_mov_b32_dpp v112, v92 quad_perm:[0,1,2,3] row_mask:0xf bank_mask:0x8
	v_mov_b32_dpp v113, v93 quad_perm:[0,1,2,3] row_mask:0xf bank_mask:0x8
	v_mov_b32_dpp v114, v94 quad_perm:[0,1,2,3] row_mask:0xf bank_mask:0x8
	v_mov_b32_dpp v115, v95 quad_perm:[0,1,2,3] row_mask:0xf bank_mask:0x8
	v_pk_fma_f32 v[254:255], v[206:207], v[88:89], v[136:137]
	v_pk_fma_f32 v[148:149], v[208:209], v[90:91], v[138:139]
	v_fmac_f32_dpp v254, v88, v190 row_shr:1 row_mask:0xf bank_mask:0xf
	v_fmac_f32_dpp v255, v89, v191 row_shr:1 row_mask:0xf bank_mask:0xf
	v_fmac_f32_dpp v148, v90, v192 row_shr:1 row_mask:0xf bank_mask:0xf
	v_fmac_f32_dpp v149, v91, v193 row_shr:1 row_mask:0xf bank_mask:0xf
; __device__ __forceinline__ f32x2 gelu_pk(f32x2 v) {
;     const f32x2 av = __builtin_elementwise_abs(v), d = av * 0.2316418882f + 1.0f;
;     __device__ __forceinline__ void operator()(const f32x4 (&acc)[2][2][4][2], const Unit& u, int wr, int wc, int fr, int fq) const {
;     ...
; #pragma unroll
;                     for (int m = 0; m < 4; ++m) {
;                         f32x4 cv;
;                         if (!samp) {
;                             const f32x4 prev = m ? v[m - 1] : hv;
; #pragma unroll
;                             for (int e = 0; e < 4; ++e) {
;                                 const int vi = __float_as_int(v[m][e]), pi = __float_as_int(prev[e]);
;                                 const int o1 = __builtin_amdgcn_mov_dpp(pi, 0x121, 0xf, 0xf, false);
;                                 const int o2 = __builtin_amdgcn_mov_dpp(pi, 0x122, 0xf, 0xf, false);
;                                 const float p1 = __int_as_float(__builtin_amdgcn_update_dpp(o1, vi, 0x111, 0xf, 0xf, false));
;                                 const float p2 = __int_as_float(__builtin_amdgcn_update_dpp(o2, vi, 0x112, 0xf, 0xf, false));
;                                 cv[e] = cb[e] + cw0[e] * p2 + cw1[e] * p1 + cw2[e] * v[m][e];
;                             }
;                         } else {
;                             const int ns = rowb + 16 * m + fr - MP;
;                             f32x4 s0 = (f32x4){0.f, 0.f, 0.f, 0.f}, s1 = s0;
;                             if (ns < NS) {
;                                 s0 = *(const f32x4*)(state + (size_t)(ns * 2 + 0) * FF2 + oc); s1 = *(const f32x4*)(state + (size_t)(ns * 2 + 1) * FF2 + oc);
;                                 *(f32x4*)(ncs + (size_t)(ns * 2 + 0) * FF2 + oc) = s1; *(f32x4*)(ncs + (size_t)(ns * 2 + 1) * FF2 + oc) = v[m];
;                             }
;                             cv = cb + cw0 * s0 + cw1 * s1 + cw2 * v[m];
;                         }
;                         if (bj == 0) cg[m] = gelu4(cv);
;                         else {
;                             const f32x4 r = cg[m] * cv;
;                             v2u w; w.x = cvt_pk_bf16(r[0], r[1]); w.y = cvt_pk_bf16(r[2], r[3]);
;                             *(v2u*)(ACT + (size_t)(rowb + 16 * m + fr) * FF + 128 * u.pn + 32 * wc + 8 * fq + 4 * n) = w;
;                         }
	v_fmac_f32_dpp v254, v88, v174 row_shr:2 row_mask:0xf bank_mask:0xf
	v_fmac_f32_dpp v255, v89, v175 row_shr:2 row_mask:0xf bank_mask:0xf
	v_fmac_f32_dpp v148, v90, v176 row_shr:2 row_mask:0xf bank_mask:0xf
	v_fmac_f32_dpp v149, v91, v177 row_shr:2 row_mask:0xf bank_mask:0xf
	v_fmac_f32_dpp v254, v112, v190 row_ror:1 row_mask:0xf bank_mask:0x1
	v_fmac_f32_dpp v255, v113, v191 row_ror:1 row_mask:0xf bank_mask:0x1
	v_fmac_f32_dpp v148, v114, v192 row_ror:1 row_mask:0xf bank_mask:0x1
	v_fmac_f32_dpp v149, v115, v193 row_ror:1 row_mask:0xf bank_mask:0x1
	v_fmac_f32_dpp v254, v112, v174 row_ror:2 row_mask:0xf bank_mask:0x1
	v_fmac_f32_dpp v255, v113, v175 row_ror:2 row_mask:0xf bank_mask:0x1
	v_fmac_f32_dpp v148, v114, v176 row_ror:2 row_mask:0xf bank_mask:0x1
	v_fmac_f32_dpp v149, v115, v177 row_ror:2 row_mask:0xf bank_mask:0x1
	v_fma_f32 v246, |v254|, s38, 1.0
	v_fma_f32 v247, |v255|, s38, 1.0
	v_fma_f32 v248, |v148|, s38, 1.0
	v_fma_f32 v249, |v149|, s38, 1.0
	v_pk_mul_f32 v[250:251], v[254:255], v[254:255]
	v_pk_mul_f32 v[252:253], v[148:149], v[148:149]
	v_rcp_f32_e32 v246, v246
	v_rcp_f32_e32 v247, v247
	v_rcp_f32_e32 v248, v248
	v_rcp_f32_e32 v249, v249
	v_pk_mul_f32 v[250:251], v[250:251], s[72:73] op_sel_hi:[1,0]
	v_pk_mul_f32 v[252:253], v[252:253], s[72:73] op_sel_hi:[1,0]
	v_exp_f32_e32 v250, v250
	v_exp_f32_e32 v251, v251
	v_exp_f32_e32 v252, v252
	v_exp_f32_e32 v253, v253
	v_pk_fma_f32 v[238:239], v[246:247], s[56:57], v[218:219] op_sel:[0,0,1] op_sel_hi:[1,0,1]
	v_pk_fma_f32 v[240:241], v[248:249], s[56:57], v[218:219] op_sel:[0,0,1] op_sel_hi:[1,0,1]
	v_pk_fma_f32 v[238:239], v[246:247], v[238:239], s[66:67] op_sel_hi:[1,1,0]
	v_pk_fma_f32 v[240:241], v[248:249], v[240:241], s[66:67] op_sel_hi:[1,1,0]
	v_pk_fma_f32 v[238:239], v[246:247], v[238:239], s[68:69] op_sel_hi:[1,1,0]
	v_pk_fma_f32 v[240:241], v[248:249], v[240:241], s[68:69] op_sel_hi:[1,1,0]
	v_pk_fma_f32 v[238:239], v[246:247], v[238:239], s[70:71] op_sel_hi:[1,1,0]
	v_pk_fma_f32 v[240:241], v[248:249], v[240:241], s[70:71] op_sel_hi:[1,1,0]
	v_pk_mul_f32 v[238:239], v[246:247], v[238:239]
	v_pk_mul_f32 v[240:241], v[248:249], v[240:241]
	v_pk_mul_f32 v[238:239], v[250:251], v[238:239]
	v_pk_mul_f32 v[240:241], v[252:253], v[240:241]
	v_max_f32_e32 v246, 0, v254
	v_max_f32_e32 v247, 0, v255
	v_max_f32_e32 v248, 0, v148
	v_max_f32_e32 v249, 0, v149
	v_fma_f32 v238, -|v254|, v238, v246
	v_fma_f32 v239, -|v255|, v239, v247
	v_fma_f32 v240, -|v148|, v240, v248
	v_fma_f32 v241, -|v149|, v241, v249
	v_mov_b32_dpp v112, v76 quad_perm:[0,1,2,3] row_mask:0xf bank_mask:0x8
	v_mov_b32_dpp v113, v77 quad_perm:[0,1,2,3] row_mask:0xf bank_mask:0x8
	v_mov_b32_dpp v114, v78 quad_perm:[0,1,2,3] row_mask:0xf bank_mask:0x8
	v_mov_b32_dpp v115, v79 quad_perm:[0,1,2,3] row_mask:0xf bank_mask:0x8
	v_pk_fma_f32 v[254:255], v[128:129], v[72:73], v[144:145]
	v_pk_fma_f32 v[148:149], v[130:131], v[74:75], v[146:147]
	v_fmac_f32_dpp v254, v72, v198 row_shr:1 row_mask:0xf bank_mask:0xf
	v_fmac_f32_dpp v255, v73, v199 row_shr:1 row_mask:0xf bank_mask:0xf
	v_fmac_f32_dpp v148, v74, v200 row_shr:1 row_mask:0xf bank_mask:0xf
	v_fmac_f32_dpp v149, v75, v201 row_shr:1 row_mask:0xf bank_mask:0xf
	v_fmac_f32_dpp v254, v72, v182 row_shr:2 row_mask:0xf bank_mask:0xf
	v_fmac_f32_dpp v255, v73, v183 row_shr:2 row_mask:0xf bank_mask:0xf
	v_fmac_f32_dpp v148, v74, v184 row_shr:2 row_mask:0xf bank_mask:0xf
	v_fmac_f32_dpp v149, v75, v185 row_shr:2 row_mask:0xf bank_mask:0xf
	v_fmac_f32_dpp v254, v112, v198 row_ror:1 row_mask:0xf bank_mask:0x1
	v_fmac_f32_dpp v255, v113, v199 row_ror:1 row_mask:0xf bank_mask:0x1
	v_fmac_f32_dpp v148, v114, v200 row_ror:1 row_mask:0xf bank_mask:0x1
	v_fmac_f32_dpp v149, v115, v201 row_ror:1 row_mask:0xf bank_mask:0x1
	v_fmac_f32_dpp v254, v112, v182 row_ror:2 row_mask:0xf bank_mask:0x1
	v_fmac_f32_dpp v255, v113, v183 row_ror:2 row_mask:0xf bank_mask:0x1
	v_fmac_f32_dpp v148, v114, v184 row_ror:2 row_mask:0xf bank_mask:0x1
	v_fmac_f32_dpp v149, v115, v185 row_ror:2 row_mask:0xf bank_mask:0x1
	v_pk_mul_f32 v[254:255], v[238:239], v[254:255]
	v_pk_mul_f32 v[148:149], v[240:241], v[148:149]
	v_cvt_pk_bf16_f32 v244, v254, v255
	v_cvt_pk_bf16_f32 v245, v148, v149
	s_add_u32 s56, s46, 0x16000
	s_addc_u32 s57, s47, 0
	global_store_dwordx4 v151, v[242:245], s[56:57]
	s_mov_b32 s56, 0x3f07dc22
	v_mov_b32_dpp v112, v48 quad_perm:[0,1,2,3] row_mask:0xf bank_mask:0x8
	v_mov_b32_dpp v113, v49 quad_perm:[0,1,2,3] row_mask:0xf bank_mask:0x8
	v_mov_b32_dpp v114, v50 quad_perm:[0,1,2,3] row_mask:0xf bank_mask:0x8
	v_mov_b32_dpp v115, v51 quad_perm:[0,1,2,3] row_mask:0xf bank_mask:0x8
	v_pk_fma_f32 v[254:255], v[202:203], v[56:57], v[132:133]
	v_pk_fma_f32 v[148:149], v[204:205], v[58:59], v[134:135]
	v_fmac_f32_dpp v254, v56, v186 row_shr:1 row_mask:0xf bank_mask:0xf
	v_fmac_f32_dpp v255, v57, v187 row_shr:1 row_mask:0xf bank_mask:0xf
	v_fmac_f32_dpp v148, v58, v188 row_shr:1 row_mask:0xf bank_mask:0xf
	v_fmac_f32_dpp v149, v59, v189 row_shr:1 row_mask:0xf bank_mask:0xf
	v_fmac_f32_dpp v254, v56, v170 row_shr:2 row_mask:0xf bank_mask:0xf
	v_fmac_f32_dpp v255, v57, v171 row_shr:2 row_mask:0xf bank_mask:0xf
	v_fmac_f32_dpp v148, v58, v172 row_shr:2 row_mask:0xf bank_mask:0xf
	v_fmac_f32_dpp v149, v59, v173 row_shr:2 row_mask:0xf bank_mask:0xf
	v_fmac_f32_dpp v254, v112, v186 row_ror:1 row_mask:0xf bank_mask:0x1
	v_fmac_f32_dpp v255, v113, v187 row_ror:1 row_mask:0xf bank_mask:0x1
	v_fmac_f32_dpp v148, v114, v188 row_ror:1 row_mask:0xf bank_mask:0x1
	v_fmac_f32_dpp v149, v115, v189 row_ror:1 row_mask:0xf bank_mask:0x1
	v_fmac_f32_dpp v254, v112, v170 row_ror:2 row_mask:0xf bank_mask:0x1
; __device__ __forceinline__ f32x2 gelu_pk(f32x2 v) {
;     const f32x2 av = __builtin_elementwise_abs(v), d = av * 0.2316418882f + 1.0f;
;     __device__ __forceinline__ void operator()(const f32x4 (&acc)[2][2][4][2], const Unit& u, int wr, int wc, int fr, int fq) const {
;     ...
; #pragma unroll
;                     for (int m = 0; m < 4; ++m) {
;                         f32x4 cv;
;                         if (!samp) {
;                             const f32x4 prev = m ? v[m - 1] : hv;
; #pragma unroll
;                             for (int e = 0; e < 4; ++e) {
;                                 const int vi = __float_as_int(v[m][e]), pi = __float_as_int(prev[e]);
;                                 const int o1 = __builtin_amdgcn_mov_dpp(pi, 0x121, 0xf, 0xf, false);
;                                 const int o2 = __builtin_amdgcn_mov_dpp(pi, 0x122, 0xf, 0xf, false);
;                                 const float p1 = __int_as_float(__builtin_amdgcn_update_dpp(o1, vi, 0x111, 0xf, 0xf, false));
;                                 const float p2 = __int_as_float(__builtin_amdgcn_update_dpp(o2, vi, 0x112, 0xf, 0xf, false));
;                                 cv[e] = cb[e] + cw0[e] * p2 + cw1[e] * p1 + cw2[e] * v[m][e];
;                             }
;                         } else {
;                             const int ns = rowb + 16 * m + fr - MP;
;                             f32x4 s0 = (f32x4){0.f, 0.f, 0.f, 0.f}, s1 = s0;
;                             if (ns < NS) {
;                                 s0 = *(const f32x4*)(state + (size_t)(ns * 2 + 0) * FF2 + oc); s1 = *(const f32x4*)(state + (size_t)(ns * 2 + 1) * FF2 + oc);
;                                 *(f32x4*)(ncs + (size_t)(ns * 2 + 0) * FF2 + oc) = s1; *(f32x4*)(ncs + (size_t)(ns * 2 + 1) * FF2 + oc) = v[m];
;                             }
;                             cv = cb + cw0 * s0 + cw1 * s1 + cw2 * v[m];
;                         }
;                         if (bj == 0) cg[m] = gelu4(cv);
;                         else {
;                             const f32x4 r = cg[m] * cv;
;                             v2u w; w.x = cvt_pk_bf16(r[0], r[1]); w.y = cvt_pk_bf16(r[2], r[3]);
;                             *(v2u*)(ACT + (size_t)(rowb + 16 * m + fr) * FF + 128 * u.pn + 32 * wc + 8 * fq + 4 * n) = w;
;                         }
	v_fmac_f32_dpp v255, v113, v171 row_ror:2 row_mask:0xf bank_mask:0x1
	v_fmac_f32_dpp v148, v114, v172 row_ror:2 row_mask:0xf bank_mask:0x1
	v_fmac_f32_dpp v149, v115, v173 row_ror:2 row_mask:0xf bank_mask:0x1
	v_fma_f32 v246, |v254|, s38, 1.0
	v_fma_f32 v247, |v255|, s38, 1.0
	v_fma_f32 v248, |v148|, s38, 1.0
	v_fma_f32 v249, |v149|, s38, 1.0
	v_pk_mul_f32 v[250:251], v[254:255], v[254:255]
	v_pk_mul_f32 v[252:253], v[148:149], v[148:149]
	v_rcp_f32_e32 v246, v246
	v_rcp_f32_e32 v247, v247
	v_rcp_f32_e32 v248, v248
	v_rcp_f32_e32 v249, v249
	v_pk_mul_f32 v[250:251], v[250:251], s[72:73] op_sel_hi:[1,0]
	v_pk_mul_f32 v[252:253], v[252:253], s[72:73] op_sel_hi:[1,0]
	v_exp_f32_e32 v250, v250
	v_exp_f32_e32 v251, v251
	v_exp_f32_e32 v252, v252
	v_exp_f32_e32 v253, v253
	v_pk_fma_f32 v[238:239], v[246:247], s[56:57], v[218:219] op_sel:[0,0,1] op_sel_hi:[1,0,1]
	v_pk_fma_f32 v[240:241], v[248:249], s[56:57], v[218:219] op_sel:[0,0,1] op_sel_hi:[1,0,1]
	v_pk_fma_f32 v[238:239], v[246:247], v[238:239], s[66:67] op_sel_hi:[1,1,0]
	v_pk_fma_f32 v[240:241], v[248:249], v[240:241], s[66:67] op_sel_hi:[1,1,0]
	v_pk_fma_f32 v[238:239], v[246:247], v[238:239], s[68:69] op_sel_hi:[1,1,0]
	v_pk_fma_f32 v[240:241], v[248:249], v[240:241], s[68:69] op_sel_hi:[1,1,0]
	v_pk_fma_f32 v[238:239], v[246:247], v[238:239], s[70:71] op_sel_hi:[1,1,0]
	v_pk_fma_f32 v[240:241], v[248:249], v[240:241], s[70:71] op_sel_hi:[1,1,0]
	v_pk_mul_f32 v[238:239], v[246:247], v[238:239]
	v_pk_mul_f32 v[240:241], v[248:249], v[240:241]
	v_pk_mul_f32 v[238:239], v[250:251], v[238:239]
	v_pk_mul_f32 v[240:241], v[252:253], v[240:241]
	v_max_f32_e32 v246, 0, v254
	v_max_f32_e32 v247, 0, v255
	v_max_f32_e32 v248, 0, v148
	v_max_f32_e32 v249, 0, v149
	v_fma_f32 v238, -|v254|, v238, v246
	v_fma_f32 v239, -|v255|, v239, v247
	v_fma_f32 v240, -|v148|, v240, v248
	v_fma_f32 v241, -|v149|, v241, v249
	v_mov_b32_dpp v112, v32 quad_perm:[0,1,2,3] row_mask:0xf bank_mask:0x8
	v_mov_b32_dpp v113, v33 quad_perm:[0,1,2,3] row_mask:0xf bank_mask:0x8
	v_mov_b32_dpp v114, v34 quad_perm:[0,1,2,3] row_mask:0xf bank_mask:0x8
	v_mov_b32_dpp v115, v35 quad_perm:[0,1,2,3] row_mask:0xf bank_mask:0x8
	v_pk_fma_f32 v[254:255], v[210:211], v[40:41], v[140:141]
	v_pk_fma_f32 v[148:149], v[212:213], v[42:43], v[142:143]
	v_fmac_f32_dpp v254, v40, v194 row_shr:1 row_mask:0xf bank_mask:0xf
	v_fmac_f32_dpp v255, v41, v195 row_shr:1 row_mask:0xf bank_mask:0xf
	v_fmac_f32_dpp v148, v42, v196 row_shr:1 row_mask:0xf bank_mask:0xf
	v_fmac_f32_dpp v149, v43, v197 row_shr:1 row_mask:0xf bank_mask:0xf
	v_fmac_f32_dpp v254, v40, v178 row_shr:2 row_mask:0xf bank_mask:0xf
	v_fmac_f32_dpp v255, v41, v179 row_shr:2 row_mask:0xf bank_mask:0xf
	v_fmac_f32_dpp v148, v42, v180 row_shr:2 row_mask:0xf bank_mask:0xf
	v_fmac_f32_dpp v149, v43, v181 row_shr:2 row_mask:0xf bank_mask:0xf
	v_fmac_f32_dpp v254, v112, v194 row_ror:1 row_mask:0xf bank_mask:0x1
	v_fmac_f32_dpp v255, v113, v195 row_ror:1 row_mask:0xf bank_mask:0x1
	v_fmac_f32_dpp v148, v114, v196 row_ror:1 row_mask:0xf bank_mask:0x1
	v_fmac_f32_dpp v149, v115, v197 row_ror:1 row_mask:0xf bank_mask:0x1
	v_fmac_f32_dpp v254, v112, v178 row_ror:2 row_mask:0xf bank_mask:0x1
	v_fmac_f32_dpp v255, v113, v179 row_ror:2 row_mask:0xf bank_mask:0x1
	v_fmac_f32_dpp v148, v114, v180 row_ror:2 row_mask:0xf bank_mask:0x1
	v_fmac_f32_dpp v149, v115, v181 row_ror:2 row_mask:0xf bank_mask:0x1
	v_pk_mul_f32 v[254:255], v[238:239], v[254:255]
	v_pk_mul_f32 v[148:149], v[240:241], v[148:149]
	v_cvt_pk_bf16_f32 v242, v254, v255
	v_cvt_pk_bf16_f32 v243, v148, v149
	v_mov_b32_dpp v112, v16 quad_perm:[0,1,2,3] row_mask:0xf bank_mask:0x8
	v_mov_b32_dpp v113, v17 quad_perm:[0,1,2,3] row_mask:0xf bank_mask:0x8
	v_mov_b32_dpp v114, v18 quad_perm:[0,1,2,3] row_mask:0xf bank_mask:0x8
	v_mov_b32_dpp v115, v19 quad_perm:[0,1,2,3] row_mask:0xf bank_mask:0x8
	v_pk_fma_f32 v[254:255], v[206:207], v[24:25], v[136:137]
	v_pk_fma_f32 v[148:149], v[208:209], v[26:27], v[138:139]
	v_fmac_f32_dpp v254, v24, v190 row_shr:1 row_mask:0xf bank_mask:0xf
	v_fmac_f32_dpp v255, v25, v191 row_shr:1 row_mask:0xf bank_mask:0xf
	v_fmac_f32_dpp v148, v26, v192 row_shr:1 row_mask:0xf bank_mask:0xf
	v_fmac_f32_dpp v149, v27, v193 row_shr:1 row_mask:0xf bank_mask:0xf
	v_fmac_f32_dpp v254, v24, v174 row_shr:2 row_mask:0xf bank_mask:0xf
	v_fmac_f32_dpp v255, v25, v175 row_shr:2 row_mask:0xf bank_mask:0xf
	v_fmac_f32_dpp v148, v26, v176 row_shr:2 row_mask:0xf bank_mask:0xf
	v_fmac_f32_dpp v149, v27, v177 row_shr:2 row_mask:0xf bank_mask:0xf
	v_fmac_f32_dpp v254, v112, v190 row_ror:1 row_mask:0xf bank_mask:0x1
	v_fmac_f32_dpp v255, v113, v191 row_ror:1 row_mask:0xf bank_mask:0x1
	v_fmac_f32_dpp v148, v114, v192 row_ror:1 row_mask:0xf bank_mask:0x1
	v_fmac_f32_dpp v149, v115, v193 row_ror:1 row_mask:0xf bank_mask:0x1
	v_fmac_f32_dpp v254, v112, v174 row_ror:2 row_mask:0xf bank_mask:0x1
	v_fmac_f32_dpp v255, v113, v175 row_ror:2 row_mask:0xf bank_mask:0x1
	v_fmac_f32_dpp v148, v114, v176 row_ror:2 row_mask:0xf bank_mask:0x1
	v_fmac_f32_dpp v149, v115, v177 row_ror:2 row_mask:0xf bank_mask:0x1
	v_fma_f32 v246, |v254|, s38, 1.0
	v_fma_f32 v247, |v255|, s38, 1.0
	v_fma_f32 v248, |v148|, s38, 1.0
	v_fma_f32 v249, |v149|, s38, 1.0
	v_pk_mul_f32 v[250:251], v[254:255], v[254:255]
	v_pk_mul_f32 v[252:253], v[148:149], v[148:149]
	v_rcp_f32_e32 v246, v246
	v_rcp_f32_e32 v247, v247
	v_rcp_f32_e32 v248, v248
	v_rcp_f32_e32 v249, v249
	v_pk_mul_f32 v[250:251], v[250:251], s[72:73] op_sel_hi:[1,0]
	v_pk_mul_f32 v[252:253], v[252:253], s[72:73] op_sel_hi:[1,0]
	v_exp_f32_e32 v250, v250
	v_exp_f32_e32 v251, v251
	v_exp_f32_e32 v252, v252
; __device__ __forceinline__ f32x2 gelu_pk(f32x2 v) {
;     const f32x2 av = __builtin_elementwise_abs(v), d = av * 0.2316418882f + 1.0f;
;     __device__ __forceinline__ void operator()(const f32x4 (&acc)[2][2][4][2], const Unit& u, int wr, int wc, int fr, int fq) const {
;     ...
; #pragma unroll
;                     for (int m = 0; m < 4; ++m) {
;                         f32x4 cv;
;                         if (!samp) {
;                             const f32x4 prev = m ? v[m - 1] : hv;
; #pragma unroll
;                             for (int e = 0; e < 4; ++e) {
;                                 const int vi = __float_as_int(v[m][e]), pi = __float_as_int(prev[e]);
;                                 const int o1 = __builtin_amdgcn_mov_dpp(pi, 0x121, 0xf, 0xf, false);
;                                 const int o2 = __builtin_amdgcn_mov_dpp(pi, 0x122, 0xf, 0xf, false);
;                                 const float p1 = __int_as_float(__builtin_amdgcn_update_dpp(o1, vi, 0x111, 0xf, 0xf, false));
;                                 const float p2 = __int_as_float(__builtin_amdgcn_update_dpp(o2, vi, 0x112, 0xf, 0xf, false));
;                                 cv[e] = cb[e] + cw0[e] * p2 + cw1[e] * p1 + cw2[e] * v[m][e];
;                             }
;                         } else {
;                             const int ns = rowb + 16 * m + fr - MP;
;                             f32x4 s0 = (f32x4){0.f, 0.f, 0.f, 0.f}, s1 = s0;
;                             if (ns < NS) {
;                                 s0 = *(const f32x4*)(state + (size_t)(ns * 2 + 0) * FF2 + oc); s1 = *(const f32x4*)(state + (size_t)(ns * 2 + 1) * FF2 + oc);
;                                 *(f32x4*)(ncs + (size_t)(ns * 2 + 0) * FF2 + oc) = s1; *(f32x4*)(ncs + (size_t)(ns * 2 + 1) * FF2 + oc) = v[m];
;                             }
;                             cv = cb + cw0 * s0 + cw1 * s1 + cw2 * v[m];
;                         }
;                         if (bj == 0) cg[m] = gelu4(cv);
;                         else {
;                             const f32x4 r = cg[m] * cv;
;                             v2u w; w.x = cvt_pk_bf16(r[0], r[1]); w.y = cvt_pk_bf16(r[2], r[3]);
;                             *(v2u*)(ACT + (size_t)(rowb + 16 * m + fr) * FF + 128 * u.pn + 32 * wc + 8 * fq + 4 * n) = w;
;                         }
	v_exp_f32_e32 v253, v253
	v_pk_fma_f32 v[238:239], v[246:247], s[56:57], v[218:219] op_sel:[0,0,1] op_sel_hi:[1,0,1]
	v_pk_fma_f32 v[240:241], v[248:249], s[56:57], v[218:219] op_sel:[0,0,1] op_sel_hi:[1,0,1]
	v_pk_fma_f32 v[238:239], v[246:247], v[238:239], s[66:67] op_sel_hi:[1,1,0]
	v_pk_fma_f32 v[240:241], v[248:249], v[240:241], s[66:67] op_sel_hi:[1,1,0]
	v_pk_fma_f32 v[238:239], v[246:247], v[238:239], s[68:69] op_sel_hi:[1,1,0]
	v_pk_fma_f32 v[240:241], v[248:249], v[240:241], s[68:69] op_sel_hi:[1,1,0]
	v_pk_fma_f32 v[238:239], v[246:247], v[238:239], s[70:71] op_sel_hi:[1,1,0]
	v_pk_fma_f32 v[240:241], v[248:249], v[240:241], s[70:71] op_sel_hi:[1,1,0]
	v_pk_mul_f32 v[238:239], v[246:247], v[238:239]
	v_pk_mul_f32 v[240:241], v[248:249], v[240:241]
	v_pk_mul_f32 v[238:239], v[250:251], v[238:239]
	v_pk_mul_f32 v[240:241], v[252:253], v[240:241]
	v_max_f32_e32 v246, 0, v254
	v_max_f32_e32 v247, 0, v255
	v_max_f32_e32 v248, 0, v148
	v_max_f32_e32 v249, 0, v149
	v_fma_f32 v238, -|v254|, v238, v246
	v_fma_f32 v239, -|v255|, v239, v247
	v_fma_f32 v240, -|v148|, v240, v248
	v_fma_f32 v241, -|v149|, v241, v249
	v_mov_b32_dpp v112, v0 quad_perm:[0,1,2,3] row_mask:0xf bank_mask:0x8
	v_mov_b32_dpp v113, v1 quad_perm:[0,1,2,3] row_mask:0xf bank_mask:0x8
	v_mov_b32_dpp v114, v2 quad_perm:[0,1,2,3] row_mask:0xf bank_mask:0x8
	v_mov_b32_dpp v115, v3 quad_perm:[0,1,2,3] row_mask:0xf bank_mask:0x8
	v_pk_fma_f32 v[254:255], v[128:129], v[8:9], v[144:145]
	v_pk_fma_f32 v[148:149], v[130:131], v[10:11], v[146:147]
	v_fmac_f32_dpp v254, v8, v198 row_shr:1 row_mask:0xf bank_mask:0xf
	v_fmac_f32_dpp v255, v9, v199 row_shr:1 row_mask:0xf bank_mask:0xf
	v_fmac_f32_dpp v148, v10, v200 row_shr:1 row_mask:0xf bank_mask:0xf
	v_fmac_f32_dpp v149, v11, v201 row_shr:1 row_mask:0xf bank_mask:0xf
	v_fmac_f32_dpp v254, v8, v182 row_shr:2 row_mask:0xf bank_mask:0xf
	v_fmac_f32_dpp v255, v9, v183 row_shr:2 row_mask:0xf bank_mask:0xf
	v_fmac_f32_dpp v148, v10, v184 row_shr:2 row_mask:0xf bank_mask:0xf
	v_fmac_f32_dpp v149, v11, v185 row_shr:2 row_mask:0xf bank_mask:0xf
	v_fmac_f32_dpp v254, v112, v198 row_ror:1 row_mask:0xf bank_mask:0x1
	v_fmac_f32_dpp v255, v113, v199 row_ror:1 row_mask:0xf bank_mask:0x1
	v_fmac_f32_dpp v148, v114, v200 row_ror:1 row_mask:0xf bank_mask:0x1
	v_fmac_f32_dpp v149, v115, v201 row_ror:1 row_mask:0xf bank_mask:0x1
	v_fmac_f32_dpp v254, v112, v182 row_ror:2 row_mask:0xf bank_mask:0x1
	v_fmac_f32_dpp v255, v113, v183 row_ror:2 row_mask:0xf bank_mask:0x1
	v_fmac_f32_dpp v148, v114, v184 row_ror:2 row_mask:0xf bank_mask:0x1
	v_fmac_f32_dpp v149, v115, v185 row_ror:2 row_mask:0xf bank_mask:0x1
	v_pk_mul_f32 v[254:255], v[238:239], v[254:255]
	v_pk_mul_f32 v[148:149], v[240:241], v[148:149]
	v_cvt_pk_bf16_f32 v244, v254, v255
	v_cvt_pk_bf16_f32 v245, v148, v149
	s_add_u32 s56, s46, 0xf2000
	s_addc_u32 s57, s47, 0
	global_store_dwordx4 v151, v[242:245], s[56:57]
	s_mov_b32 s56, 0x3f07dc22
	v_mov_b32_dpp v112, v52 quad_perm:[0,1,2,3] row_mask:0xf bank_mask:0x8
	v_mov_b32_dpp v113, v53 quad_perm:[0,1,2,3] row_mask:0xf bank_mask:0x8
	v_mov_b32_dpp v114, v54 quad_perm:[0,1,2,3] row_mask:0xf bank_mask:0x8
	v_mov_b32_dpp v115, v55 quad_perm:[0,1,2,3] row_mask:0xf bank_mask:0x8
	v_pk_fma_f32 v[254:255], v[202:203], v[48:49], v[132:133]
	v_pk_fma_f32 v[148:149], v[204:205], v[50:51], v[134:135]
	v_fmac_f32_dpp v254, v48, v186 row_shr:1 row_mask:0xf bank_mask:0xf
	v_fmac_f32_dpp v255, v49, v187 row_shr:1 row_mask:0xf bank_mask:0xf
	v_fmac_f32_dpp v148, v50, v188 row_shr:1 row_mask:0xf bank_mask:0xf
	v_fmac_f32_dpp v149, v51, v189 row_shr:1 row_mask:0xf bank_mask:0xf
	v_fmac_f32_dpp v254, v48, v170 row_shr:2 row_mask:0xf bank_mask:0xf
	v_fmac_f32_dpp v255, v49, v171 row_shr:2 row_mask:0xf bank_mask:0xf
	v_fmac_f32_dpp v148, v50, v172 row_shr:2 row_mask:0xf bank_mask:0xf
	v_fmac_f32_dpp v149, v51, v173 row_shr:2 row_mask:0xf bank_mask:0xf
	v_fmac_f32_dpp v254, v112, v186 row_ror:1 row_mask:0xf bank_mask:0x1
	v_fmac_f32_dpp v255, v113, v187 row_ror:1 row_mask:0xf bank_mask:0x1
	v_fmac_f32_dpp v148, v114, v188 row_ror:1 row_mask:0xf bank_mask:0x1
	v_fmac_f32_dpp v149, v115, v189 row_ror:1 row_mask:0xf bank_mask:0x1
	v_fmac_f32_dpp v254, v112, v170 row_ror:2 row_mask:0xf bank_mask:0x1
	v_fmac_f32_dpp v255, v113, v171 row_ror:2 row_mask:0xf bank_mask:0x1
	v_fmac_f32_dpp v148, v114, v172 row_ror:2 row_mask:0xf bank_mask:0x1
	v_fmac_f32_dpp v149, v115, v173 row_ror:2 row_mask:0xf bank_mask:0x1
	v_fma_f32 v246, |v254|, s38, 1.0
	v_fma_f32 v247, |v255|, s38, 1.0
	v_fma_f32 v248, |v148|, s38, 1.0
	v_fma_f32 v249, |v149|, s38, 1.0
	v_pk_mul_f32 v[250:251], v[254:255], v[254:255]
	v_pk_mul_f32 v[252:253], v[148:149], v[148:149]
	v_rcp_f32_e32 v246, v246
	v_rcp_f32_e32 v247, v247
	v_rcp_f32_e32 v248, v248
	v_rcp_f32_e32 v249, v249
	v_pk_mul_f32 v[250:251], v[250:251], s[72:73] op_sel_hi:[1,0]
	v_pk_mul_f32 v[252:253], v[252:253], s[72:73] op_sel_hi:[1,0]
	v_exp_f32_e32 v250, v250
	v_exp_f32_e32 v251, v251
	v_exp_f32_e32 v252, v252
	v_exp_f32_e32 v253, v253
	v_pk_fma_f32 v[238:239], v[246:247], s[56:57], v[218:219] op_sel:[0,0,1] op_sel_hi:[1,0,1]
	v_pk_fma_f32 v[240:241], v[248:249], s[56:57], v[218:219] op_sel:[0,0,1] op_sel_hi:[1,0,1]
	v_pk_fma_f32 v[238:239], v[246:247], v[238:239], s[66:67] op_sel_hi:[1,1,0]
	v_pk_fma_f32 v[240:241], v[248:249], v[240:241], s[66:67] op_sel_hi:[1,1,0]
	v_pk_fma_f32 v[238:239], v[246:247], v[238:239], s[68:69] op_sel_hi:[1,1,0]
	v_pk_fma_f32 v[240:241], v[248:249], v[240:241], s[68:69] op_sel_hi:[1,1,0]
	v_pk_fma_f32 v[238:239], v[246:247], v[238:239], s[70:71] op_sel_hi:[1,1,0]
	v_pk_fma_f32 v[240:241], v[248:249], v[240:241], s[70:71] op_sel_hi:[1,1,0]
; __device__ __forceinline__ f32x2 gelu_pk(f32x2 v) {
;     const f32x2 av = __builtin_elementwise_abs(v), d = av * 0.2316418882f + 1.0f;
;     __device__ __forceinline__ void operator()(const f32x4 (&acc)[2][2][4][2], const Unit& u, int wr, int wc, int fr, int fq) const {
;     ...
; #pragma unroll
;                     for (int m = 0; m < 4; ++m) {
;                         f32x4 cv;
;                         if (!samp) {
;                             const f32x4 prev = m ? v[m - 1] : hv;
; #pragma unroll
;                             for (int e = 0; e < 4; ++e) {
;                                 const int vi = __float_as_int(v[m][e]), pi = __float_as_int(prev[e]);
;                                 const int o1 = __builtin_amdgcn_mov_dpp(pi, 0x121, 0xf, 0xf, false);
;                                 const int o2 = __builtin_amdgcn_mov_dpp(pi, 0x122, 0xf, 0xf, false);
;                                 const float p1 = __int_as_float(__builtin_amdgcn_update_dpp(o1, vi, 0x111, 0xf, 0xf, false));
;                                 const float p2 = __int_as_float(__builtin_amdgcn_update_dpp(o2, vi, 0x112, 0xf, 0xf, false));
;                                 cv[e] = cb[e] + cw0[e] * p2 + cw1[e] * p1 + cw2[e] * v[m][e];
;                             }
;                         } else {
;                             const int ns = rowb + 16 * m + fr - MP;
;                             f32x4 s0 = (f32x4){0.f, 0.f, 0.f, 0.f}, s1 = s0;
;                             if (ns < NS) {
;                                 s0 = *(const f32x4*)(state + (size_t)(ns * 2 + 0) * FF2 + oc); s1 = *(const f32x4*)(state + (size_t)(ns * 2 + 1) * FF2 + oc);
;                                 *(f32x4*)(ncs + (size_t)(ns * 2 + 0) * FF2 + oc) = s1; *(f32x4*)(ncs + (size_t)(ns * 2 + 1) * FF2 + oc) = v[m];
;                             }
;                             cv = cb + cw0 * s0 + cw1 * s1 + cw2 * v[m];
;                         }
;                         if (bj == 0) cg[m] = gelu4(cv);
;                         else {
;                             const f32x4 r = cg[m] * cv;
;                             v2u w; w.x = cvt_pk_bf16(r[0], r[1]); w.y = cvt_pk_bf16(r[2], r[3]);
;                             *(v2u*)(ACT + (size_t)(rowb + 16 * m + fr) * FF + 128 * u.pn + 32 * wc + 8 * fq + 4 * n) = w;
;                         }
	v_pk_mul_f32 v[238:239], v[246:247], v[238:239]
	v_pk_mul_f32 v[240:241], v[248:249], v[240:241]
	v_pk_mul_f32 v[238:239], v[250:251], v[238:239]
	v_pk_mul_f32 v[240:241], v[252:253], v[240:241]
	v_max_f32_e32 v246, 0, v254
	v_max_f32_e32 v247, 0, v255
	v_max_f32_e32 v248, 0, v148
	v_max_f32_e32 v249, 0, v149
	v_fma_f32 v238, -|v254|, v238, v246
	v_fma_f32 v239, -|v255|, v239, v247
	v_fma_f32 v240, -|v148|, v240, v248
	v_fma_f32 v241, -|v149|, v241, v249
	v_mov_b32_dpp v112, v36 quad_perm:[0,1,2,3] row_mask:0xf bank_mask:0x8
	v_mov_b32_dpp v113, v37 quad_perm:[0,1,2,3] row_mask:0xf bank_mask:0x8
	v_mov_b32_dpp v114, v38 quad_perm:[0,1,2,3] row_mask:0xf bank_mask:0x8
	v_mov_b32_dpp v115, v39 quad_perm:[0,1,2,3] row_mask:0xf bank_mask:0x8
	v_pk_fma_f32 v[254:255], v[210:211], v[32:33], v[140:141]
	v_pk_fma_f32 v[148:149], v[212:213], v[34:35], v[142:143]
	v_fmac_f32_dpp v254, v32, v194 row_shr:1 row_mask:0xf bank_mask:0xf
	v_fmac_f32_dpp v255, v33, v195 row_shr:1 row_mask:0xf bank_mask:0xf
	v_fmac_f32_dpp v148, v34, v196 row_shr:1 row_mask:0xf bank_mask:0xf
	v_fmac_f32_dpp v149, v35, v197 row_shr:1 row_mask:0xf bank_mask:0xf
	v_fmac_f32_dpp v254, v32, v178 row_shr:2 row_mask:0xf bank_mask:0xf
	v_fmac_f32_dpp v255, v33, v179 row_shr:2 row_mask:0xf bank_mask:0xf
	v_fmac_f32_dpp v148, v34, v180 row_shr:2 row_mask:0xf bank_mask:0xf
	v_fmac_f32_dpp v149, v35, v181 row_shr:2 row_mask:0xf bank_mask:0xf
	v_fmac_f32_dpp v254, v112, v194 row_ror:1 row_mask:0xf bank_mask:0x1
	v_fmac_f32_dpp v255, v113, v195 row_ror:1 row_mask:0xf bank_mask:0x1
	v_fmac_f32_dpp v148, v114, v196 row_ror:1 row_mask:0xf bank_mask:0x1
	v_fmac_f32_dpp v149, v115, v197 row_ror:1 row_mask:0xf bank_mask:0x1
	v_fmac_f32_dpp v254, v112, v178 row_ror:2 row_mask:0xf bank_mask:0x1
	v_fmac_f32_dpp v255, v113, v179 row_ror:2 row_mask:0xf bank_mask:0x1
	v_fmac_f32_dpp v148, v114, v180 row_ror:2 row_mask:0xf bank_mask:0x1
	v_fmac_f32_dpp v149, v115, v181 row_ror:2 row_mask:0xf bank_mask:0x1
	v_pk_mul_f32 v[254:255], v[238:239], v[254:255]
	v_pk_mul_f32 v[148:149], v[240:241], v[148:149]
	v_cvt_pk_bf16_f32 v242, v254, v255
	v_cvt_pk_bf16_f32 v243, v148, v149
	v_mov_b32_dpp v112, v20 quad_perm:[0,1,2,3] row_mask:0xf bank_mask:0x8
	v_mov_b32_dpp v113, v21 quad_perm:[0,1,2,3] row_mask:0xf bank_mask:0x8
	v_mov_b32_dpp v114, v22 quad_perm:[0,1,2,3] row_mask:0xf bank_mask:0x8
	v_mov_b32_dpp v115, v23 quad_perm:[0,1,2,3] row_mask:0xf bank_mask:0x8
	v_pk_fma_f32 v[254:255], v[206:207], v[16:17], v[136:137]
	v_pk_fma_f32 v[148:149], v[208:209], v[18:19], v[138:139]
	v_fmac_f32_dpp v254, v16, v190 row_shr:1 row_mask:0xf bank_mask:0xf
	v_fmac_f32_dpp v255, v17, v191 row_shr:1 row_mask:0xf bank_mask:0xf
	v_fmac_f32_dpp v148, v18, v192 row_shr:1 row_mask:0xf bank_mask:0xf
	v_fmac_f32_dpp v149, v19, v193 row_shr:1 row_mask:0xf bank_mask:0xf
	v_fmac_f32_dpp v254, v16, v174 row_shr:2 row_mask:0xf bank_mask:0xf
	v_fmac_f32_dpp v255, v17, v175 row_shr:2 row_mask:0xf bank_mask:0xf
	v_fmac_f32_dpp v148, v18, v176 row_shr:2 row_mask:0xf bank_mask:0xf
	v_fmac_f32_dpp v149, v19, v177 row_shr:2 row_mask:0xf bank_mask:0xf
	v_fmac_f32_dpp v254, v112, v190 row_ror:1 row_mask:0xf bank_mask:0x1
	v_fmac_f32_dpp v255, v113, v191 row_ror:1 row_mask:0xf bank_mask:0x1
	v_fmac_f32_dpp v148, v114, v192 row_ror:1 row_mask:0xf bank_mask:0x1
	v_fmac_f32_dpp v149, v115, v193 row_ror:1 row_mask:0xf bank_mask:0x1
	v_fmac_f32_dpp v254, v112, v174 row_ror:2 row_mask:0xf bank_mask:0x1
	v_fmac_f32_dpp v255, v113, v175 row_ror:2 row_mask:0xf bank_mask:0x1
	v_fmac_f32_dpp v148, v114, v176 row_ror:2 row_mask:0xf bank_mask:0x1
	v_fmac_f32_dpp v149, v115, v177 row_ror:2 row_mask:0xf bank_mask:0x1
	v_fma_f32 v246, |v254|, s38, 1.0
	v_fma_f32 v247, |v255|, s38, 1.0
	v_fma_f32 v248, |v148|, s38, 1.0
	v_fma_f32 v249, |v149|, s38, 1.0
	v_pk_mul_f32 v[250:251], v[254:255], v[254:255]
	v_pk_mul_f32 v[252:253], v[148:149], v[148:149]
	v_rcp_f32_e32 v246, v246
	v_rcp_f32_e32 v247, v247
	v_rcp_f32_e32 v248, v248
	v_rcp_f32_e32 v249, v249
	v_pk_mul_f32 v[250:251], v[250:251], s[72:73] op_sel_hi:[1,0]
	v_pk_mul_f32 v[252:253], v[252:253], s[72:73] op_sel_hi:[1,0]
	v_exp_f32_e32 v250, v250
	v_exp_f32_e32 v251, v251
	v_exp_f32_e32 v252, v252
	v_exp_f32_e32 v253, v253
	v_pk_fma_f32 v[238:239], v[246:247], s[56:57], v[218:219] op_sel:[0,0,1] op_sel_hi:[1,0,1]
	v_pk_fma_f32 v[240:241], v[248:249], s[56:57], v[218:219] op_sel:[0,0,1] op_sel_hi:[1,0,1]
	v_pk_fma_f32 v[238:239], v[246:247], v[238:239], s[66:67] op_sel_hi:[1,1,0]
	v_pk_fma_f32 v[240:241], v[248:249], v[240:241], s[66:67] op_sel_hi:[1,1,0]
	v_pk_fma_f32 v[238:239], v[246:247], v[238:239], s[68:69] op_sel_hi:[1,1,0]
	v_pk_fma_f32 v[240:241], v[248:249], v[240:241], s[68:69] op_sel_hi:[1,1,0]
	v_pk_fma_f32 v[238:239], v[246:247], v[238:239], s[70:71] op_sel_hi:[1,1,0]
	v_pk_fma_f32 v[240:241], v[248:249], v[240:241], s[70:71] op_sel_hi:[1,1,0]
	v_pk_mul_f32 v[238:239], v[246:247], v[238:239]
	v_pk_mul_f32 v[240:241], v[248:249], v[240:241]
	v_pk_mul_f32 v[238:239], v[250:251], v[238:239]
	v_pk_mul_f32 v[240:241], v[252:253], v[240:241]
	v_max_f32_e32 v246, 0, v254
	v_max_f32_e32 v247, 0, v255
	v_max_f32_e32 v248, 0, v148
	v_max_f32_e32 v249, 0, v149
	v_fma_f32 v238, -|v254|, v238, v246
	v_fma_f32 v239, -|v255|, v239, v247
	v_fma_f32 v240, -|v148|, v240, v248
	v_fma_f32 v241, -|v149|, v241, v249
	v_mov_b32_dpp v112, v4 quad_perm:[0,1,2,3] row_mask:0xf bank_mask:0x8
	v_mov_b32_dpp v113, v5 quad_perm:[0,1,2,3] row_mask:0xf bank_mask:0x8
	v_mov_b32_dpp v114, v6 quad_perm:[0,1,2,3] row_mask:0xf bank_mask:0x8
	v_mov_b32_dpp v115, v7 quad_perm:[0,1,2,3] row_mask:0xf bank_mask:0x8
; __device__ __forceinline__ f32x2 gelu_pk(f32x2 v) {
;     const f32x2 av = __builtin_elementwise_abs(v), d = av * 0.2316418882f + 1.0f;
;     __device__ __forceinline__ void operator()(const f32x4 (&acc)[2][2][4][2], const Unit& u, int wr, int wc, int fr, int fq) const {
;     ...
; #pragma unroll
;                     for (int m = 0; m < 4; ++m) {
;                         f32x4 cv;
;                         if (!samp) {
;                             const f32x4 prev = m ? v[m - 1] : hv;
; #pragma unroll
;                             for (int e = 0; e < 4; ++e) {
;                                 const int vi = __float_as_int(v[m][e]), pi = __float_as_int(prev[e]);
;                                 const int o1 = __builtin_amdgcn_mov_dpp(pi, 0x121, 0xf, 0xf, false);
;                                 const int o2 = __builtin_amdgcn_mov_dpp(pi, 0x122, 0xf, 0xf, false);
;                                 const float p1 = __int_as_float(__builtin_amdgcn_update_dpp(o1, vi, 0x111, 0xf, 0xf, false));
;                                 const float p2 = __int_as_float(__builtin_amdgcn_update_dpp(o2, vi, 0x112, 0xf, 0xf, false));
;                                 cv[e] = cb[e] + cw0[e] * p2 + cw1[e] * p1 + cw2[e] * v[m][e];
;                             }
;                         } else {
;                             const int ns = rowb + 16 * m + fr - MP;
;                             f32x4 s0 = (f32x4){0.f, 0.f, 0.f, 0.f}, s1 = s0;
;                             if (ns < NS) {
;                                 s0 = *(const f32x4*)(state + (size_t)(ns * 2 + 0) * FF2 + oc); s1 = *(const f32x4*)(state + (size_t)(ns * 2 + 1) * FF2 + oc);
;                                 *(f32x4*)(ncs + (size_t)(ns * 2 + 0) * FF2 + oc) = s1; *(f32x4*)(ncs + (size_t)(ns * 2 + 1) * FF2 + oc) = v[m];
;                             }
;                             cv = cb + cw0 * s0 + cw1 * s1 + cw2 * v[m];
;                         }
;                         if (bj == 0) cg[m] = gelu4(cv);
;                         else {
;                             const f32x4 r = cg[m] * cv;
;                             v2u w; w.x = cvt_pk_bf16(r[0], r[1]); w.y = cvt_pk_bf16(r[2], r[3]);
;                             *(v2u*)(ACT + (size_t)(rowb + 16 * m + fr) * FF + 128 * u.pn + 32 * wc + 8 * fq + 4 * n) = w;
;                         }
	v_pk_fma_f32 v[254:255], v[128:129], v[0:1], v[144:145]
	v_pk_fma_f32 v[148:149], v[130:131], v[2:3], v[146:147]
	v_fmac_f32_dpp v254, v0, v198 row_shr:1 row_mask:0xf bank_mask:0xf
	v_fmac_f32_dpp v255, v1, v199 row_shr:1 row_mask:0xf bank_mask:0xf
	v_fmac_f32_dpp v148, v2, v200 row_shr:1 row_mask:0xf bank_mask:0xf
	v_fmac_f32_dpp v149, v3, v201 row_shr:1 row_mask:0xf bank_mask:0xf
	v_fmac_f32_dpp v254, v0, v182 row_shr:2 row_mask:0xf bank_mask:0xf
	v_fmac_f32_dpp v255, v1, v183 row_shr:2 row_mask:0xf bank_mask:0xf
	v_fmac_f32_dpp v148, v2, v184 row_shr:2 row_mask:0xf bank_mask:0xf
	v_fmac_f32_dpp v149, v3, v185 row_shr:2 row_mask:0xf bank_mask:0xf
	v_fmac_f32_dpp v254, v112, v198 row_ror:1 row_mask:0xf bank_mask:0x1
	v_fmac_f32_dpp v255, v113, v199 row_ror:1 row_mask:0xf bank_mask:0x1
	v_fmac_f32_dpp v148, v114, v200 row_ror:1 row_mask:0xf bank_mask:0x1
	v_fmac_f32_dpp v149, v115, v201 row_ror:1 row_mask:0xf bank_mask:0x1
	v_fmac_f32_dpp v254, v112, v182 row_ror:2 row_mask:0xf bank_mask:0x1
	v_fmac_f32_dpp v255, v113, v183 row_ror:2 row_mask:0xf bank_mask:0x1
	v_fmac_f32_dpp v148, v114, v184 row_ror:2 row_mask:0xf bank_mask:0x1
	v_fmac_f32_dpp v149, v115, v185 row_ror:2 row_mask:0xf bank_mask:0x1
	v_pk_mul_f32 v[254:255], v[238:239], v[254:255]
	v_pk_mul_f32 v[148:149], v[240:241], v[148:149]
	v_cvt_pk_bf16_f32 v244, v254, v255
	v_cvt_pk_bf16_f32 v245, v148, v149
	s_add_u32 s56, s46, 0xdc000
	s_addc_u32 s57, s47, 0
	global_store_dwordx4 v151, v[242:245], s[56:57]
	s_mov_b32 s56, 0x3f07dc22
	v_mov_b32_dpp v112, v60 quad_perm:[0,1,2,3] row_mask:0xf bank_mask:0x8
	v_mov_b32_dpp v113, v61 quad_perm:[0,1,2,3] row_mask:0xf bank_mask:0x8
	v_mov_b32_dpp v114, v62 quad_perm:[0,1,2,3] row_mask:0xf bank_mask:0x8
	v_mov_b32_dpp v115, v63 quad_perm:[0,1,2,3] row_mask:0xf bank_mask:0x8
	v_pk_fma_f32 v[254:255], v[202:203], v[52:53], v[132:133]
	v_pk_fma_f32 v[148:149], v[204:205], v[54:55], v[134:135]
	v_fmac_f32_dpp v254, v52, v186 row_shr:1 row_mask:0xf bank_mask:0xf
	v_fmac_f32_dpp v255, v53, v187 row_shr:1 row_mask:0xf bank_mask:0xf
	v_fmac_f32_dpp v148, v54, v188 row_shr:1 row_mask:0xf bank_mask:0xf
	v_fmac_f32_dpp v149, v55, v189 row_shr:1 row_mask:0xf bank_mask:0xf
	v_fmac_f32_dpp v254, v52, v170 row_shr:2 row_mask:0xf bank_mask:0xf
	v_fmac_f32_dpp v255, v53, v171 row_shr:2 row_mask:0xf bank_mask:0xf
	v_fmac_f32_dpp v148, v54, v172 row_shr:2 row_mask:0xf bank_mask:0xf
	v_fmac_f32_dpp v149, v55, v173 row_shr:2 row_mask:0xf bank_mask:0xf
	v_fmac_f32_dpp v254, v112, v186 row_ror:1 row_mask:0xf bank_mask:0x1
	v_fmac_f32_dpp v255, v113, v187 row_ror:1 row_mask:0xf bank_mask:0x1
	v_fmac_f32_dpp v148, v114, v188 row_ror:1 row_mask:0xf bank_mask:0x1
	v_fmac_f32_dpp v149, v115, v189 row_ror:1 row_mask:0xf bank_mask:0x1
	v_fmac_f32_dpp v254, v112, v170 row_ror:2 row_mask:0xf bank_mask:0x1
	v_fmac_f32_dpp v255, v113, v171 row_ror:2 row_mask:0xf bank_mask:0x1
	v_fmac_f32_dpp v148, v114, v172 row_ror:2 row_mask:0xf bank_mask:0x1
	v_fmac_f32_dpp v149, v115, v173 row_ror:2 row_mask:0xf bank_mask:0x1
	v_fma_f32 v246, |v254|, s38, 1.0
	v_fma_f32 v247, |v255|, s38, 1.0
	v_fma_f32 v248, |v148|, s38, 1.0
	v_fma_f32 v249, |v149|, s38, 1.0
	v_pk_mul_f32 v[250:251], v[254:255], v[254:255]
	v_pk_mul_f32 v[252:253], v[148:149], v[148:149]
	v_rcp_f32_e32 v246, v246
	v_rcp_f32_e32 v247, v247
	v_rcp_f32_e32 v248, v248
	v_rcp_f32_e32 v249, v249
	v_pk_mul_f32 v[250:251], v[250:251], s[72:73] op_sel_hi:[1,0]
	v_pk_mul_f32 v[252:253], v[252:253], s[72:73] op_sel_hi:[1,0]
	v_exp_f32_e32 v250, v250
	v_exp_f32_e32 v251, v251
	v_exp_f32_e32 v252, v252
	v_exp_f32_e32 v253, v253
	v_pk_fma_f32 v[238:239], v[246:247], s[56:57], v[218:219] op_sel:[0,0,1] op_sel_hi:[1,0,1]
	v_pk_fma_f32 v[240:241], v[248:249], s[56:57], v[218:219] op_sel:[0,0,1] op_sel_hi:[1,0,1]
	v_pk_fma_f32 v[238:239], v[246:247], v[238:239], s[66:67] op_sel_hi:[1,1,0]
	v_pk_fma_f32 v[240:241], v[248:249], v[240:241], s[66:67] op_sel_hi:[1,1,0]
	v_pk_fma_f32 v[238:239], v[246:247], v[238:239], s[68:69] op_sel_hi:[1,1,0]
	v_pk_fma_f32 v[240:241], v[248:249], v[240:241], s[68:69] op_sel_hi:[1,1,0]
	v_pk_fma_f32 v[238:239], v[246:247], v[238:239], s[70:71] op_sel_hi:[1,1,0]
	v_pk_fma_f32 v[240:241], v[248:249], v[240:241], s[70:71] op_sel_hi:[1,1,0]
	v_pk_mul_f32 v[238:239], v[246:247], v[238:239]
	v_pk_mul_f32 v[240:241], v[248:249], v[240:241]
	v_pk_mul_f32 v[238:239], v[250:251], v[238:239]
	v_pk_mul_f32 v[240:241], v[252:253], v[240:241]
	v_max_f32_e32 v246, 0, v254
	v_max_f32_e32 v247, 0, v255
	v_max_f32_e32 v248, 0, v148
	v_max_f32_e32 v249, 0, v149
	v_fma_f32 v238, -|v254|, v238, v246
	v_fma_f32 v239, -|v255|, v239, v247
	v_fma_f32 v240, -|v148|, v240, v248
	v_fma_f32 v241, -|v149|, v241, v249
	v_mov_b32_dpp v112, v44 quad_perm:[0,1,2,3] row_mask:0xf bank_mask:0x8
	v_mov_b32_dpp v113, v45 quad_perm:[0,1,2,3] row_mask:0xf bank_mask:0x8
	v_mov_b32_dpp v114, v46 quad_perm:[0,1,2,3] row_mask:0xf bank_mask:0x8
	v_mov_b32_dpp v115, v47 quad_perm:[0,1,2,3] row_mask:0xf bank_mask:0x8
	v_pk_fma_f32 v[254:255], v[210:211], v[36:37], v[140:141]
	v_pk_fma_f32 v[148:149], v[212:213], v[38:39], v[142:143]
	v_fmac_f32_dpp v254, v36, v194 row_shr:1 row_mask:0xf bank_mask:0xf
	v_fmac_f32_dpp v255, v37, v195 row_shr:1 row_mask:0xf bank_mask:0xf
	v_fmac_f32_dpp v148, v38, v196 row_shr:1 row_mask:0xf bank_mask:0xf
	v_fmac_f32_dpp v149, v39, v197 row_shr:1 row_mask:0xf bank_mask:0xf
	v_fmac_f32_dpp v254, v36, v178 row_shr:2 row_mask:0xf bank_mask:0xf
	v_fmac_f32_dpp v255, v37, v179 row_shr:2 row_mask:0xf bank_mask:0xf
	v_fmac_f32_dpp v148, v38, v180 row_shr:2 row_mask:0xf bank_mask:0xf
	v_fmac_f32_dpp v149, v39, v181 row_shr:2 row_mask:0xf bank_mask:0xf
;     __device__ __forceinline__ void operator()(const f32x4 (&acc)[2][2][4][2], const Unit& u, int wr, int wc, int fr, int fq) const {
;     ...
;         if (!halo_ok) {
;             if (threadIdx.x < 64) { unsigned sp = 0;
;     ...
; #pragma unroll
;                     for (int m = 0; m < 4; ++m) {
;                         f32x4 cv;
;                         if (!samp) {
;                             const f32x4 prev = m ? v[m - 1] : hv;
; #pragma unroll
;                             for (int e = 0; e < 4; ++e) {
;                                 const int vi = __float_as_int(v[m][e]), pi = __float_as_int(prev[e]);
;                                 const int o1 = __builtin_amdgcn_mov_dpp(pi, 0x121, 0xf, 0xf, false);
;                                 const int o2 = __builtin_amdgcn_mov_dpp(pi, 0x122, 0xf, 0xf, false);
;                                 const float p1 = __int_as_float(__builtin_amdgcn_update_dpp(o1, vi, 0x111, 0xf, 0xf, false));
;                                 const float p2 = __int_as_float(__builtin_amdgcn_update_dpp(o2, vi, 0x112, 0xf, 0xf, false));
;                                 cv[e] = cb[e] + cw0[e] * p2 + cw1[e] * p1 + cw2[e] * v[m][e];
;                             }
;                         } else {
;                             const int ns = rowb + 16 * m + fr - MP;
;                             f32x4 s0 = (f32x4){0.f, 0.f, 0.f, 0.f}, s1 = s0;
;                             if (ns < NS) {
;                                 s0 = *(const f32x4*)(state + (size_t)(ns * 2 + 0) * FF2 + oc); s1 = *(const f32x4*)(state + (size_t)(ns * 2 + 1) * FF2 + oc);
;                                 *(f32x4*)(ncs + (size_t)(ns * 2 + 0) * FF2 + oc) = s1; *(f32x4*)(ncs + (size_t)(ns * 2 + 1) * FF2 + oc) = v[m];
;                             }
;                             cv = cb + cw0 * s0 + cw1 * s1 + cw2 * v[m];
;                         }
;                         if (bj == 0) cg[m] = gelu4(cv);
;                         else {
;                             const f32x4 r = cg[m] * cv;
;                             v2u w; w.x = cvt_pk_bf16(r[0], r[1]); w.y = cvt_pk_bf16(r[2], r[3]);
;                             *(v2u*)(ACT + (size_t)(rowb + 16 * m + fr) * FF + 128 * u.pn + 32 * wc + 8 * fq + 4 * n) = w;
;                         }
	v_fmac_f32_dpp v254, v112, v194 row_ror:1 row_mask:0xf bank_mask:0x1
	v_fmac_f32_dpp v255, v113, v195 row_ror:1 row_mask:0xf bank_mask:0x1
	v_fmac_f32_dpp v148, v114, v196 row_ror:1 row_mask:0xf bank_mask:0x1
	v_fmac_f32_dpp v149, v115, v197 row_ror:1 row_mask:0xf bank_mask:0x1
	v_fmac_f32_dpp v254, v112, v178 row_ror:2 row_mask:0xf bank_mask:0x1
	v_fmac_f32_dpp v255, v113, v179 row_ror:2 row_mask:0xf bank_mask:0x1
	v_fmac_f32_dpp v148, v114, v180 row_ror:2 row_mask:0xf bank_mask:0x1
	v_fmac_f32_dpp v149, v115, v181 row_ror:2 row_mask:0xf bank_mask:0x1
	v_pk_mul_f32 v[254:255], v[238:239], v[254:255]
	v_pk_mul_f32 v[148:149], v[240:241], v[148:149]
	v_cvt_pk_bf16_f32 v242, v254, v255
	v_cvt_pk_bf16_f32 v243, v148, v149
	v_mov_b32_dpp v112, v28 quad_perm:[0,1,2,3] row_mask:0xf bank_mask:0x8
	v_mov_b32_dpp v113, v29 quad_perm:[0,1,2,3] row_mask:0xf bank_mask:0x8
	v_mov_b32_dpp v114, v30 quad_perm:[0,1,2,3] row_mask:0xf bank_mask:0x8
	v_mov_b32_dpp v115, v31 quad_perm:[0,1,2,3] row_mask:0xf bank_mask:0x8
	v_pk_fma_f32 v[254:255], v[206:207], v[20:21], v[136:137]
	v_pk_fma_f32 v[148:149], v[208:209], v[22:23], v[138:139]
	v_fmac_f32_dpp v254, v20, v190 row_shr:1 row_mask:0xf bank_mask:0xf
	v_fmac_f32_dpp v255, v21, v191 row_shr:1 row_mask:0xf bank_mask:0xf
	v_fmac_f32_dpp v148, v22, v192 row_shr:1 row_mask:0xf bank_mask:0xf
	v_fmac_f32_dpp v149, v23, v193 row_shr:1 row_mask:0xf bank_mask:0xf
	v_fmac_f32_dpp v254, v20, v174 row_shr:2 row_mask:0xf bank_mask:0xf
	v_fmac_f32_dpp v255, v21, v175 row_shr:2 row_mask:0xf bank_mask:0xf
	v_fmac_f32_dpp v148, v22, v176 row_shr:2 row_mask:0xf bank_mask:0xf
	v_fmac_f32_dpp v149, v23, v177 row_shr:2 row_mask:0xf bank_mask:0xf
	v_fmac_f32_dpp v254, v112, v190 row_ror:1 row_mask:0xf bank_mask:0x1
	v_fmac_f32_dpp v255, v113, v191 row_ror:1 row_mask:0xf bank_mask:0x1
	v_fmac_f32_dpp v148, v114, v192 row_ror:1 row_mask:0xf bank_mask:0x1
	v_fmac_f32_dpp v149, v115, v193 row_ror:1 row_mask:0xf bank_mask:0x1
	v_fmac_f32_dpp v254, v112, v174 row_ror:2 row_mask:0xf bank_mask:0x1
	v_fmac_f32_dpp v255, v113, v175 row_ror:2 row_mask:0xf bank_mask:0x1
	v_fmac_f32_dpp v148, v114, v176 row_ror:2 row_mask:0xf bank_mask:0x1
	v_fmac_f32_dpp v149, v115, v177 row_ror:2 row_mask:0xf bank_mask:0x1
	v_fma_f32 v246, |v254|, s38, 1.0
	v_fma_f32 v247, |v255|, s38, 1.0
	v_fma_f32 v248, |v148|, s38, 1.0
	v_fma_f32 v249, |v149|, s38, 1.0
	v_pk_mul_f32 v[250:251], v[254:255], v[254:255]
	v_pk_mul_f32 v[252:253], v[148:149], v[148:149]
	v_rcp_f32_e32 v246, v246
	v_rcp_f32_e32 v247, v247
	v_rcp_f32_e32 v248, v248
	v_rcp_f32_e32 v249, v249
	v_pk_mul_f32 v[250:251], v[250:251], s[72:73] op_sel_hi:[1,0]
	v_pk_mul_f32 v[252:253], v[252:253], s[72:73] op_sel_hi:[1,0]
	v_exp_f32_e32 v250, v250
	v_exp_f32_e32 v251, v251
	v_exp_f32_e32 v252, v252
	v_exp_f32_e32 v253, v253
	v_pk_fma_f32 v[238:239], v[246:247], s[56:57], v[218:219] op_sel:[0,0,1] op_sel_hi:[1,0,1]
	v_pk_fma_f32 v[240:241], v[248:249], s[56:57], v[218:219] op_sel:[0,0,1] op_sel_hi:[1,0,1]
	v_pk_fma_f32 v[238:239], v[246:247], v[238:239], s[66:67] op_sel_hi:[1,1,0]
	v_pk_fma_f32 v[240:241], v[248:249], v[240:241], s[66:67] op_sel_hi:[1,1,0]
	v_pk_fma_f32 v[238:239], v[246:247], v[238:239], s[68:69] op_sel_hi:[1,1,0]
	v_pk_fma_f32 v[240:241], v[248:249], v[240:241], s[68:69] op_sel_hi:[1,1,0]
	v_pk_fma_f32 v[238:239], v[246:247], v[238:239], s[70:71] op_sel_hi:[1,1,0]
	v_pk_fma_f32 v[240:241], v[248:249], v[240:241], s[70:71] op_sel_hi:[1,1,0]
	v_pk_mul_f32 v[238:239], v[246:247], v[238:239]
	v_pk_mul_f32 v[240:241], v[248:249], v[240:241]
	v_pk_mul_f32 v[238:239], v[250:251], v[238:239]
	v_pk_mul_f32 v[240:241], v[252:253], v[240:241]
	v_max_f32_e32 v246, 0, v254
	v_max_f32_e32 v247, 0, v255
	v_max_f32_e32 v248, 0, v148
	v_max_f32_e32 v249, 0, v149
	v_fma_f32 v238, -|v254|, v238, v246
	v_fma_f32 v239, -|v255|, v239, v247
	v_fma_f32 v240, -|v148|, v240, v248
	v_fma_f32 v241, -|v149|, v241, v249
	v_mov_b32_dpp v112, v12 quad_perm:[0,1,2,3] row_mask:0xf bank_mask:0x8
	v_mov_b32_dpp v113, v13 quad_perm:[0,1,2,3] row_mask:0xf bank_mask:0x8
	v_mov_b32_dpp v114, v14 quad_perm:[0,1,2,3] row_mask:0xf bank_mask:0x8
	v_mov_b32_dpp v115, v15 quad_perm:[0,1,2,3] row_mask:0xf bank_mask:0x8
	v_pk_fma_f32 v[254:255], v[128:129], v[4:5], v[144:145]
	v_pk_fma_f32 v[148:149], v[130:131], v[6:7], v[146:147]
	v_fmac_f32_dpp v254, v4, v198 row_shr:1 row_mask:0xf bank_mask:0xf
	v_fmac_f32_dpp v255, v5, v199 row_shr:1 row_mask:0xf bank_mask:0xf
	v_fmac_f32_dpp v148, v6, v200 row_shr:1 row_mask:0xf bank_mask:0xf
	v_fmac_f32_dpp v149, v7, v201 row_shr:1 row_mask:0xf bank_mask:0xf
	v_fmac_f32_dpp v254, v4, v182 row_shr:2 row_mask:0xf bank_mask:0xf
	v_fmac_f32_dpp v255, v5, v183 row_shr:2 row_mask:0xf bank_mask:0xf
	v_fmac_f32_dpp v148, v6, v184 row_shr:2 row_mask:0xf bank_mask:0xf
	v_fmac_f32_dpp v149, v7, v185 row_shr:2 row_mask:0xf bank_mask:0xf
	v_fmac_f32_dpp v254, v112, v198 row_ror:1 row_mask:0xf bank_mask:0x1
	v_fmac_f32_dpp v255, v113, v199 row_ror:1 row_mask:0xf bank_mask:0x1
	v_fmac_f32_dpp v148, v114, v200 row_ror:1 row_mask:0xf bank_mask:0x1
	v_fmac_f32_dpp v149, v115, v201 row_ror:1 row_mask:0xf bank_mask:0x1
	v_fmac_f32_dpp v254, v112, v182 row_ror:2 row_mask:0xf bank_mask:0x1
	v_fmac_f32_dpp v255, v113, v183 row_ror:2 row_mask:0xf bank_mask:0x1
	v_fmac_f32_dpp v148, v114, v184 row_ror:2 row_mask:0xf bank_mask:0x1
	v_fmac_f32_dpp v149, v115, v185 row_ror:2 row_mask:0xf bank_mask:0x1
	v_pk_mul_f32 v[254:255], v[238:239], v[254:255]
	v_pk_mul_f32 v[148:149], v[240:241], v[148:149]
	v_cvt_pk_bf16_f32 v244, v254, v255
	v_cvt_pk_bf16_f32 v245, v148, v149
	s_add_u32 s56, s46, 0xc6000
	s_addc_u32 s57, s47, 0
	global_store_dwordx4 v151, v[242:245], s[56:57]
	s_and_b64 vcc, exec, s[86:87]
	s_cbranch_vccz .Lfe_h0b
	s_and_saveexec_b64 s[14:15], s[8:9]
	s_cbranch_execz .Lfe_hw3
	s_mov_b32 s13, 0x100001
	s_branch .Lfe_hw1

; __device__ __forceinline__ f32x2 gelu_pk(f32x2 v) {
;     const f32x2 av = __builtin_elementwise_abs(v), d = av * 0.2316418882f + 1.0f;
;     f32x2 t; t.x = __builtin_amdgcn_rcpf(d.x); t.y = __builtin_amdgcn_rcpf(d.y);
;     __device__ __forceinline__ void operator()(const f32x4 (&acc)[2][2][4][2], const Unit& u, int wr, int wc, int fr, int fq) const {
;     ...
;                     for (int m = 0; m < 4; ++m) {
;                         f32x4 cv;
;                         if (!samp) {
;                             const f32x4 prev = m ? v[m - 1] : hv;
; #pragma unroll
;                             for (int e = 0; e < 4; ++e) {
;                                 const int vi = __float_as_int(v[m][e]), pi = __float_as_int(prev[e]);
;                                 const int o1 = __builtin_amdgcn_mov_dpp(pi, 0x121, 0xf, 0xf, false);
;                                 const int o2 = __builtin_amdgcn_mov_dpp(pi, 0x122, 0xf, 0xf, false);
;                                 const float p1 = __int_as_float(__builtin_amdgcn_update_dpp(o1, vi, 0x111, 0xf, 0xf, false));
;                                 const float p2 = __int_as_float(__builtin_amdgcn_update_dpp(o2, vi, 0x112, 0xf, 0xf, false));
;                                 cv[e] = cb[e] + cw0[e] * p2 + cw1[e] * p1 + cw2[e] * v[m][e];
;                             }
;                         } else {
;                             const int ns = rowb + 16 * m + fr - MP;
;                             f32x4 s0 = (f32x4){0.f, 0.f, 0.f, 0.f}, s1 = s0;
;                             if (ns < NS) {
;                                 s0 = *(const f32x4*)(state + (size_t)(ns * 2 + 0) * FF2 + oc); s1 = *(const f32x4*)(state + (size_t)(ns * 2 + 1) * FF2 + oc);
;                                 *(f32x4*)(ncs + (size_t)(ns * 2 + 0) * FF2 + oc) = s1; *(f32x4*)(ncs + (size_t)(ns * 2 + 1) * FF2 + oc) = v[m];
;                             }
;                             cv = cb + cw0 * s0 + cw1 * s1 + cw2 * v[m];
;                         }
;                         if (bj == 0) cg[m] = gelu4(cv);
;                         else {
;                             const f32x4 r = cg[m] * cv;
;                             v2u w; w.x = cvt_pk_bf16(r[0], r[1]); w.y = cvt_pk_bf16(r[2], r[3]);
;                             *(v2u*)(ACT + (size_t)(rowb + 16 * m + fr) * FF + 128 * u.pn + 32 * wc + 8 * fq + 4 * n) = w;
;                         }
.Lfe_h0b:
	s_waitcnt vmcnt(4)
	s_mov_b32 s56, 0x3f07dc22
	v_pk_fma_f32 v[254:255], v[202:203], v[124:125], v[132:133]
	v_pk_fma_f32 v[148:149], v[204:205], v[126:127], v[134:135]
	v_fmac_f32_dpp v254, v124, v186 row_shr:1 row_mask:0xf bank_mask:0xf
	v_fmac_f32_dpp v255, v125, v187 row_shr:1 row_mask:0xf bank_mask:0xf
	v_fmac_f32_dpp v148, v126, v188 row_shr:1 row_mask:0xf bank_mask:0xf
	v_fmac_f32_dpp v149, v127, v189 row_shr:1 row_mask:0xf bank_mask:0xf
	v_fmac_f32_dpp v254, v124, v170 row_shr:2 row_mask:0xf bank_mask:0xf
	v_fmac_f32_dpp v255, v125, v171 row_shr:2 row_mask:0xf bank_mask:0xf
	v_fmac_f32_dpp v148, v126, v172 row_shr:2 row_mask:0xf bank_mask:0xf
	v_fmac_f32_dpp v149, v127, v173 row_shr:2 row_mask:0xf bank_mask:0xf
	v_fmac_f32_dpp v254, v220, v186 row_ror:1 row_mask:0xf bank_mask:0x1
	v_fmac_f32_dpp v255, v221, v187 row_ror:1 row_mask:0xf bank_mask:0x1
	v_fmac_f32_dpp v148, v222, v188 row_ror:1 row_mask:0xf bank_mask:0x1
	v_fmac_f32_dpp v149, v223, v189 row_ror:1 row_mask:0xf bank_mask:0x1
	v_fmac_f32_dpp v254, v220, v170 row_ror:2 row_mask:0xf bank_mask:0x1
	v_fmac_f32_dpp v255, v221, v171 row_ror:2 row_mask:0xf bank_mask:0x1
	v_fmac_f32_dpp v148, v222, v172 row_ror:2 row_mask:0xf bank_mask:0x1
	v_fmac_f32_dpp v149, v223, v173 row_ror:2 row_mask:0xf bank_mask:0x1
	v_fma_f32 v246, |v254|, s38, 1.0
	v_fma_f32 v247, |v255|, s38, 1.0
	v_fma_f32 v248, |v148|, s38, 1.0
	v_fma_f32 v249, |v149|, s38, 1.0
	v_pk_mul_f32 v[250:251], v[254:255], v[254:255]
	v_pk_mul_f32 v[252:253], v[148:149], v[148:149]
	v_rcp_f32_e32 v246, v246
	v_rcp_f32_e32 v247, v247
	v_rcp_f32_e32 v248, v248
	v_rcp_f32_e32 v249, v249
	v_pk_mul_f32 v[250:251], v[250:251], s[72:73] op_sel_hi:[1,0]
	v_pk_mul_f32 v[252:253], v[252:253], s[72:73] op_sel_hi:[1,0]
	v_exp_f32_e32 v250, v250
	v_exp_f32_e32 v251, v251
	v_exp_f32_e32 v252, v252
	v_exp_f32_e32 v253, v253
	v_pk_fma_f32 v[238:239], v[246:247], s[56:57], v[218:219] op_sel:[0,0,1] op_sel_hi:[1,0,1]
	v_pk_fma_f32 v[240:241], v[248:249], s[56:57], v[218:219] op_sel:[0,0,1] op_sel_hi:[1,0,1]
	v_pk_fma_f32 v[238:239], v[246:247], v[238:239], s[66:67] op_sel_hi:[1,1,0]
	v_pk_fma_f32 v[240:241], v[248:249], v[240:241], s[66:67] op_sel_hi:[1,1,0]
	v_pk_fma_f32 v[238:239], v[246:247], v[238:239], s[68:69] op_sel_hi:[1,1,0]
	v_pk_fma_f32 v[240:241], v[248:249], v[240:241], s[68:69] op_sel_hi:[1,1,0]
	v_pk_fma_f32 v[238:239], v[246:247], v[238:239], s[70:71] op_sel_hi:[1,1,0]
	v_pk_fma_f32 v[240:241], v[248:249], v[240:241], s[70:71] op_sel_hi:[1,1,0]
	v_pk_mul_f32 v[238:239], v[246:247], v[238:239]
	v_pk_mul_f32 v[240:241], v[248:249], v[240:241]
	v_pk_mul_f32 v[238:239], v[250:251], v[238:239]
	v_pk_mul_f32 v[240:241], v[252:253], v[240:241]
	v_max_f32_e32 v246, 0, v254
	v_max_f32_e32 v247, 0, v255
	v_max_f32_e32 v248, 0, v148
	v_max_f32_e32 v249, 0, v149
	v_fma_f32 v238, -|v254|, v238, v246
	v_fma_f32 v239, -|v255|, v239, v247
	v_fma_f32 v240, -|v148|, v240, v248
	v_fma_f32 v241, -|v149|, v241, v249
	v_pk_fma_f32 v[254:255], v[210:211], v[108:109], v[140:141]
	v_pk_fma_f32 v[148:149], v[212:213], v[110:111], v[142:143]
	v_fmac_f32_dpp v254, v108, v194 row_shr:1 row_mask:0xf bank_mask:0xf
	v_fmac_f32_dpp v255, v109, v195 row_shr:1 row_mask:0xf bank_mask:0xf
	v_fmac_f32_dpp v148, v110, v196 row_shr:1 row_mask:0xf bank_mask:0xf
	v_fmac_f32_dpp v149, v111, v197 row_shr:1 row_mask:0xf bank_mask:0xf
	v_fmac_f32_dpp v254, v108, v178 row_shr:2 row_mask:0xf bank_mask:0xf
	v_fmac_f32_dpp v255, v109, v179 row_shr:2 row_mask:0xf bank_mask:0xf
	v_fmac_f32_dpp v148, v110, v180 row_shr:2 row_mask:0xf bank_mask:0xf
	v_fmac_f32_dpp v149, v111, v181 row_shr:2 row_mask:0xf bank_mask:0xf
	v_fmac_f32_dpp v254, v228, v194 row_ror:1 row_mask:0xf bank_mask:0x1
	v_fmac_f32_dpp v255, v229, v195 row_ror:1 row_mask:0xf bank_mask:0x1
	v_fmac_f32_dpp v148, v230, v196 row_ror:1 row_mask:0xf bank_mask:0x1
	v_fmac_f32_dpp v149, v231, v197 row_ror:1 row_mask:0xf bank_mask:0x1
	v_fmac_f32_dpp v254, v228, v178 row_ror:2 row_mask:0xf bank_mask:0x1
	v_fmac_f32_dpp v255, v229, v179 row_ror:2 row_mask:0xf bank_mask:0x1
	v_fmac_f32_dpp v148, v230, v180 row_ror:2 row_mask:0xf bank_mask:0x1
	v_fmac_f32_dpp v149, v231, v181 row_ror:2 row_mask:0xf bank_mask:0x1
	v_pk_mul_f32 v[254:255], v[238:239], v[254:255]
	v_pk_mul_f32 v[148:149], v[240:241], v[148:149]
	v_cvt_pk_bf16_f32 v242, v254, v255
	v_cvt_pk_bf16_f32 v243, v148, v149
	v_pk_fma_f32 v[254:255], v[206:207], v[92:93], v[136:137]
	v_pk_fma_f32 v[148:149], v[208:209], v[94:95], v[138:139]
	v_fmac_f32_dpp v254, v92, v190 row_shr:1 row_mask:0xf bank_mask:0xf
	v_fmac_f32_dpp v255, v93, v191 row_shr:1 row_mask:0xf bank_mask:0xf
	v_fmac_f32_dpp v148, v94, v192 row_shr:1 row_mask:0xf bank_mask:0xf
	v_fmac_f32_dpp v149, v95, v193 row_shr:1 row_mask:0xf bank_mask:0xf
	v_fmac_f32_dpp v254, v92, v174 row_shr:2 row_mask:0xf bank_mask:0xf
	v_fmac_f32_dpp v255, v93, v175 row_shr:2 row_mask:0xf bank_mask:0xf
	v_fmac_f32_dpp v148, v94, v176 row_shr:2 row_mask:0xf bank_mask:0xf
	v_fmac_f32_dpp v149, v95, v177 row_shr:2 row_mask:0xf bank_mask:0xf
	v_fmac_f32_dpp v254, v224, v190 row_ror:1 row_mask:0xf bank_mask:0x1
	v_fmac_f32_dpp v255, v225, v191 row_ror:1 row_mask:0xf bank_mask:0x1
	v_fmac_f32_dpp v148, v226, v192 row_ror:1 row_mask:0xf bank_mask:0x1
	v_fmac_f32_dpp v149, v227, v193 row_ror:1 row_mask:0xf bank_mask:0x1
	v_fmac_f32_dpp v254, v224, v174 row_ror:2 row_mask:0xf bank_mask:0x1
	v_fmac_f32_dpp v255, v225, v175 row_ror:2 row_mask:0xf bank_mask:0x1
	v_fmac_f32_dpp v148, v226, v176 row_ror:2 row_mask:0xf bank_mask:0x1
	v_fmac_f32_dpp v149, v227, v177 row_ror:2 row_mask:0xf bank_mask:0x1
	v_fma_f32 v246, |v254|, s38, 1.0
; __device__ __forceinline__ f32x2 gelu_pk(f32x2 v) {
;     const f32x2 av = __builtin_elementwise_abs(v), d = av * 0.2316418882f + 1.0f;
;     f32x2 t; t.x = __builtin_amdgcn_rcpf(d.x); t.y = __builtin_amdgcn_rcpf(d.y);
;     __device__ __forceinline__ void operator()(const f32x4 (&acc)[2][2][4][2], const Unit& u, int wr, int wc, int fr, int fq) const {
;     ...
;                     for (int m = 0; m < 4; ++m) {
;                         f32x4 cv;
;                         if (!samp) {
;                             const f32x4 prev = m ? v[m - 1] : hv;
; #pragma unroll
;                             for (int e = 0; e < 4; ++e) {
;                                 const int vi = __float_as_int(v[m][e]), pi = __float_as_int(prev[e]);
;                                 const int o1 = __builtin_amdgcn_mov_dpp(pi, 0x121, 0xf, 0xf, false);
;                                 const int o2 = __builtin_amdgcn_mov_dpp(pi, 0x122, 0xf, 0xf, false);
;                                 const float p1 = __int_as_float(__builtin_amdgcn_update_dpp(o1, vi, 0x111, 0xf, 0xf, false));
;                                 const float p2 = __int_as_float(__builtin_amdgcn_update_dpp(o2, vi, 0x112, 0xf, 0xf, false));
;                                 cv[e] = cb[e] + cw0[e] * p2 + cw1[e] * p1 + cw2[e] * v[m][e];
;                             }
;                         } else {
;                             const int ns = rowb + 16 * m + fr - MP;
;                             f32x4 s0 = (f32x4){0.f, 0.f, 0.f, 0.f}, s1 = s0;
;                             if (ns < NS) {
;                                 s0 = *(const f32x4*)(state + (size_t)(ns * 2 + 0) * FF2 + oc); s1 = *(const f32x4*)(state + (size_t)(ns * 2 + 1) * FF2 + oc);
;                                 *(f32x4*)(ncs + (size_t)(ns * 2 + 0) * FF2 + oc) = s1; *(f32x4*)(ncs + (size_t)(ns * 2 + 1) * FF2 + oc) = v[m];
;                             }
;                             cv = cb + cw0 * s0 + cw1 * s1 + cw2 * v[m];
;                         }
;                         if (bj == 0) cg[m] = gelu4(cv);
;                         else {
;                             const f32x4 r = cg[m] * cv;
;                             v2u w; w.x = cvt_pk_bf16(r[0], r[1]); w.y = cvt_pk_bf16(r[2], r[3]);
;                             *(v2u*)(ACT + (size_t)(rowb + 16 * m + fr) * FF + 128 * u.pn + 32 * wc + 8 * fq + 4 * n) = w;
;                         }
	v_fma_f32 v247, |v255|, s38, 1.0
	v_fma_f32 v248, |v148|, s38, 1.0
	v_fma_f32 v249, |v149|, s38, 1.0
	v_pk_mul_f32 v[250:251], v[254:255], v[254:255]
	v_pk_mul_f32 v[252:253], v[148:149], v[148:149]
	v_rcp_f32_e32 v246, v246
	v_rcp_f32_e32 v247, v247
	v_rcp_f32_e32 v248, v248
	v_rcp_f32_e32 v249, v249
	v_pk_mul_f32 v[250:251], v[250:251], s[72:73] op_sel_hi:[1,0]
	v_pk_mul_f32 v[252:253], v[252:253], s[72:73] op_sel_hi:[1,0]
	v_exp_f32_e32 v250, v250
	v_exp_f32_e32 v251, v251
	v_exp_f32_e32 v252, v252
	v_exp_f32_e32 v253, v253
	v_pk_fma_f32 v[238:239], v[246:247], s[56:57], v[218:219] op_sel:[0,0,1] op_sel_hi:[1,0,1]
	v_pk_fma_f32 v[240:241], v[248:249], s[56:57], v[218:219] op_sel:[0,0,1] op_sel_hi:[1,0,1]
	v_pk_fma_f32 v[238:239], v[246:247], v[238:239], s[66:67] op_sel_hi:[1,1,0]
	v_pk_fma_f32 v[240:241], v[248:249], v[240:241], s[66:67] op_sel_hi:[1,1,0]
	v_pk_fma_f32 v[238:239], v[246:247], v[238:239], s[68:69] op_sel_hi:[1,1,0]
	v_pk_fma_f32 v[240:241], v[248:249], v[240:241], s[68:69] op_sel_hi:[1,1,0]
	v_pk_fma_f32 v[238:239], v[246:247], v[238:239], s[70:71] op_sel_hi:[1,1,0]
	v_pk_fma_f32 v[240:241], v[248:249], v[240:241], s[70:71] op_sel_hi:[1,1,0]
	v_pk_mul_f32 v[238:239], v[246:247], v[238:239]
	v_pk_mul_f32 v[240:241], v[248:249], v[240:241]
	v_pk_mul_f32 v[238:239], v[250:251], v[238:239]
	v_pk_mul_f32 v[240:241], v[252:253], v[240:241]
	v_max_f32_e32 v246, 0, v254
	v_max_f32_e32 v247, 0, v255
	v_max_f32_e32 v248, 0, v148
	v_max_f32_e32 v249, 0, v149
	v_fma_f32 v238, -|v254|, v238, v246
	v_fma_f32 v239, -|v255|, v239, v247
	v_fma_f32 v240, -|v148|, v240, v248
	v_fma_f32 v241, -|v149|, v241, v249
	v_pk_fma_f32 v[254:255], v[128:129], v[76:77], v[144:145]
	v_pk_fma_f32 v[148:149], v[130:131], v[78:79], v[146:147]
	v_fmac_f32_dpp v254, v76, v198 row_shr:1 row_mask:0xf bank_mask:0xf
	v_fmac_f32_dpp v255, v77, v199 row_shr:1 row_mask:0xf bank_mask:0xf
	v_fmac_f32_dpp v148, v78, v200 row_shr:1 row_mask:0xf bank_mask:0xf
	v_fmac_f32_dpp v149, v79, v201 row_shr:1 row_mask:0xf bank_mask:0xf
	v_fmac_f32_dpp v254, v76, v182 row_shr:2 row_mask:0xf bank_mask:0xf
	v_fmac_f32_dpp v255, v77, v183 row_shr:2 row_mask:0xf bank_mask:0xf
	v_fmac_f32_dpp v148, v78, v184 row_shr:2 row_mask:0xf bank_mask:0xf
	v_fmac_f32_dpp v149, v79, v185 row_shr:2 row_mask:0xf bank_mask:0xf
	v_fmac_f32_dpp v254, v232, v198 row_ror:1 row_mask:0xf bank_mask:0x1
	v_fmac_f32_dpp v255, v233, v199 row_ror:1 row_mask:0xf bank_mask:0x1
	v_fmac_f32_dpp v148, v234, v200 row_ror:1 row_mask:0xf bank_mask:0x1
	v_fmac_f32_dpp v149, v235, v201 row_ror:1 row_mask:0xf bank_mask:0x1
	v_fmac_f32_dpp v254, v232, v182 row_ror:2 row_mask:0xf bank_mask:0x1
	v_fmac_f32_dpp v255, v233, v183 row_ror:2 row_mask:0xf bank_mask:0x1
	v_fmac_f32_dpp v148, v234, v184 row_ror:2 row_mask:0xf bank_mask:0x1
	v_fmac_f32_dpp v149, v235, v185 row_ror:2 row_mask:0xf bank_mask:0x1
	v_pk_mul_f32 v[254:255], v[238:239], v[254:255]
	v_pk_mul_f32 v[148:149], v[240:241], v[148:149]
	v_cvt_pk_bf16_f32 v244, v254, v255
	v_cvt_pk_bf16_f32 v245, v148, v149
	global_store_dwordx4 v151, v[242:245], s[46:47]
	s_mov_b32 s56, 0x3f07dc22
	v_pk_fma_f32 v[254:255], v[202:203], v[60:61], v[132:133]
	v_pk_fma_f32 v[148:149], v[204:205], v[62:63], v[134:135]
	v_fmac_f32_dpp v254, v60, v186 row_shr:1 row_mask:0xf bank_mask:0xf
	v_fmac_f32_dpp v255, v61, v187 row_shr:1 row_mask:0xf bank_mask:0xf
	v_fmac_f32_dpp v148, v62, v188 row_shr:1 row_mask:0xf bank_mask:0xf
	v_fmac_f32_dpp v149, v63, v189 row_shr:1 row_mask:0xf bank_mask:0xf
	v_fmac_f32_dpp v254, v60, v170 row_shr:2 row_mask:0xf bank_mask:0xf
	v_fmac_f32_dpp v255, v61, v171 row_shr:2 row_mask:0xf bank_mask:0xf
	v_fmac_f32_dpp v148, v62, v172 row_shr:2 row_mask:0xf bank_mask:0xf
	v_fmac_f32_dpp v149, v63, v173 row_shr:2 row_mask:0xf bank_mask:0xf
	v_fmac_f32_dpp v254, v116, v186 row_ror:1 row_mask:0xf bank_mask:0x1
	v_fmac_f32_dpp v255, v117, v187 row_ror:1 row_mask:0xf bank_mask:0x1
	v_fmac_f32_dpp v148, v118, v188 row_ror:1 row_mask:0xf bank_mask:0x1
	v_fmac_f32_dpp v149, v119, v189 row_ror:1 row_mask:0xf bank_mask:0x1
	v_fmac_f32_dpp v254, v116, v170 row_ror:2 row_mask:0xf bank_mask:0x1
	v_fmac_f32_dpp v255, v117, v171 row_ror:2 row_mask:0xf bank_mask:0x1
	v_fmac_f32_dpp v148, v118, v172 row_ror:2 row_mask:0xf bank_mask:0x1
	v_fmac_f32_dpp v149, v119, v173 row_ror:2 row_mask:0xf bank_mask:0x1
	v_fma_f32 v246, |v254|, s38, 1.0
	v_fma_f32 v247, |v255|, s38, 1.0
	v_fma_f32 v248, |v148|, s38, 1.0
	v_fma_f32 v249, |v149|, s38, 1.0
	v_pk_mul_f32 v[250:251], v[254:255], v[254:255]
	v_pk_mul_f32 v[252:253], v[148:149], v[148:149]
	v_rcp_f32_e32 v246, v246
	v_rcp_f32_e32 v247, v247
	v_rcp_f32_e32 v248, v248
	v_rcp_f32_e32 v249, v249
	v_pk_mul_f32 v[250:251], v[250:251], s[72:73] op_sel_hi:[1,0]
	v_pk_mul_f32 v[252:253], v[252:253], s[72:73] op_sel_hi:[1,0]
	v_exp_f32_e32 v250, v250
	v_exp_f32_e32 v251, v251
	v_exp_f32_e32 v252, v252
	v_exp_f32_e32 v253, v253
	v_pk_fma_f32 v[238:239], v[246:247], s[56:57], v[218:219] op_sel:[0,0,1] op_sel_hi:[1,0,1]
	v_pk_fma_f32 v[240:241], v[248:249], s[56:57], v[218:219] op_sel:[0,0,1] op_sel_hi:[1,0,1]
	v_pk_fma_f32 v[238:239], v[246:247], v[238:239], s[66:67] op_sel_hi:[1,1,0]
	v_pk_fma_f32 v[240:241], v[248:249], v[240:241], s[66:67] op_sel_hi:[1,1,0]
	v_pk_fma_f32 v[238:239], v[246:247], v[238:239], s[68:69] op_sel_hi:[1,1,0]
	v_pk_fma_f32 v[240:241], v[248:249], v[240:241], s[68:69] op_sel_hi:[1,1,0]
	v_pk_fma_f32 v[238:239], v[246:247], v[238:239], s[70:71] op_sel_hi:[1,1,0]
	v_pk_fma_f32 v[240:241], v[248:249], v[240:241], s[70:71] op_sel_hi:[1,1,0]
	v_pk_mul_f32 v[238:239], v[246:247], v[238:239]
	v_pk_mul_f32 v[240:241], v[248:249], v[240:241]
;     __device__ __forceinline__ void operator()(const f32x4 (&acc)[2][2][4][2], const Unit& u, int wr, int wc, int fr, int fq) const {
;     ...
;                         if ((u.pm & 7) == 7 && ai == 1 && wr == 1 && fr >= 14) *(f32x4*)(ncp + (size_t)((u.pm >> 3) * 2 + (fr - 14)) * FF2 + oc) = v[3];
;                     }
; #pragma unroll
;                     for (int m = 0; m < 4; ++m) {
;                         f32x4 cv;
;                         if (!samp) {
;                             const f32x4 prev = m ? v[m - 1] : hv;
; #pragma unroll
;                             for (int e = 0; e < 4; ++e) {
;                                 const int vi = __float_as_int(v[m][e]), pi = __float_as_int(prev[e]);
;                                 const int o1 = __builtin_amdgcn_mov_dpp(pi, 0x121, 0xf, 0xf, false);
;                                 const int o2 = __builtin_amdgcn_mov_dpp(pi, 0x122, 0xf, 0xf, false);
;                                 const float p1 = __int_as_float(__builtin_amdgcn_update_dpp(o1, vi, 0x111, 0xf, 0xf, false));
;                                 const float p2 = __int_as_float(__builtin_amdgcn_update_dpp(o2, vi, 0x112, 0xf, 0xf, false));
;                                 cv[e] = cb[e] + cw0[e] * p2 + cw1[e] * p1 + cw2[e] * v[m][e];
;                             }
;                         } else {
;                             const int ns = rowb + 16 * m + fr - MP;
;                             f32x4 s0 = (f32x4){0.f, 0.f, 0.f, 0.f}, s1 = s0;
;                             if (ns < NS) {
;                                 s0 = *(const f32x4*)(state + (size_t)(ns * 2 + 0) * FF2 + oc); s1 = *(const f32x4*)(state + (size_t)(ns * 2 + 1) * FF2 + oc);
;                                 *(f32x4*)(ncs + (size_t)(ns * 2 + 0) * FF2 + oc) = s1; *(f32x4*)(ncs + (size_t)(ns * 2 + 1) * FF2 + oc) = v[m];
;                             }
;                             cv = cb + cw0 * s0 + cw1 * s1 + cw2 * v[m];
;                         }
;                         if (bj == 0) cg[m] = gelu4(cv);
;                         else {
;                             const f32x4 r = cg[m] * cv;
;                             v2u w; w.x = cvt_pk_bf16(r[0], r[1]); w.y = cvt_pk_bf16(r[2], r[3]);
;                             *(v2u*)(ACT + (size_t)(rowb + 16 * m + fr) * FF + 128 * u.pn + 32 * wc + 8 * fq + 4 * n) = w;
;                         }
	v_pk_mul_f32 v[238:239], v[250:251], v[238:239]
	v_pk_mul_f32 v[240:241], v[252:253], v[240:241]
	v_max_f32_e32 v246, 0, v254
	v_max_f32_e32 v247, 0, v255
	v_max_f32_e32 v248, 0, v148
	v_max_f32_e32 v249, 0, v149
	v_fma_f32 v238, -|v254|, v238, v246
	v_fma_f32 v239, -|v255|, v239, v247
	v_fma_f32 v240, -|v148|, v240, v248
	v_fma_f32 v241, -|v149|, v241, v249
	v_pk_fma_f32 v[254:255], v[210:211], v[44:45], v[140:141]
	v_pk_fma_f32 v[148:149], v[212:213], v[46:47], v[142:143]
	v_fmac_f32_dpp v254, v44, v194 row_shr:1 row_mask:0xf bank_mask:0xf
	v_fmac_f32_dpp v255, v45, v195 row_shr:1 row_mask:0xf bank_mask:0xf
	v_fmac_f32_dpp v148, v46, v196 row_shr:1 row_mask:0xf bank_mask:0xf
	v_fmac_f32_dpp v149, v47, v197 row_shr:1 row_mask:0xf bank_mask:0xf
	v_fmac_f32_dpp v254, v44, v178 row_shr:2 row_mask:0xf bank_mask:0xf
	v_fmac_f32_dpp v255, v45, v179 row_shr:2 row_mask:0xf bank_mask:0xf
	v_fmac_f32_dpp v148, v46, v180 row_shr:2 row_mask:0xf bank_mask:0xf
	v_fmac_f32_dpp v149, v47, v181 row_shr:2 row_mask:0xf bank_mask:0xf
	v_fmac_f32_dpp v254, v100, v194 row_ror:1 row_mask:0xf bank_mask:0x1
	v_fmac_f32_dpp v255, v101, v195 row_ror:1 row_mask:0xf bank_mask:0x1
	v_fmac_f32_dpp v148, v102, v196 row_ror:1 row_mask:0xf bank_mask:0x1
	v_fmac_f32_dpp v149, v103, v197 row_ror:1 row_mask:0xf bank_mask:0x1
	v_fmac_f32_dpp v254, v100, v178 row_ror:2 row_mask:0xf bank_mask:0x1
	v_fmac_f32_dpp v255, v101, v179 row_ror:2 row_mask:0xf bank_mask:0x1
	v_fmac_f32_dpp v148, v102, v180 row_ror:2 row_mask:0xf bank_mask:0x1
	v_fmac_f32_dpp v149, v103, v181 row_ror:2 row_mask:0xf bank_mask:0x1
	v_pk_mul_f32 v[254:255], v[238:239], v[254:255]
	v_pk_mul_f32 v[148:149], v[240:241], v[148:149]
	v_cvt_pk_bf16_f32 v242, v254, v255
	v_cvt_pk_bf16_f32 v243, v148, v149
	v_pk_fma_f32 v[254:255], v[206:207], v[28:29], v[136:137]
	v_pk_fma_f32 v[148:149], v[208:209], v[30:31], v[138:139]
	v_fmac_f32_dpp v254, v28, v190 row_shr:1 row_mask:0xf bank_mask:0xf
	v_fmac_f32_dpp v255, v29, v191 row_shr:1 row_mask:0xf bank_mask:0xf
	v_fmac_f32_dpp v148, v30, v192 row_shr:1 row_mask:0xf bank_mask:0xf
	v_fmac_f32_dpp v149, v31, v193 row_shr:1 row_mask:0xf bank_mask:0xf
	v_fmac_f32_dpp v254, v28, v174 row_shr:2 row_mask:0xf bank_mask:0xf
	v_fmac_f32_dpp v255, v29, v175 row_shr:2 row_mask:0xf bank_mask:0xf
	v_fmac_f32_dpp v148, v30, v176 row_shr:2 row_mask:0xf bank_mask:0xf
	v_fmac_f32_dpp v149, v31, v177 row_shr:2 row_mask:0xf bank_mask:0xf
	v_fmac_f32_dpp v254, v84, v190 row_ror:1 row_mask:0xf bank_mask:0x1
	v_fmac_f32_dpp v255, v85, v191 row_ror:1 row_mask:0xf bank_mask:0x1
	v_fmac_f32_dpp v148, v86, v192 row_ror:1 row_mask:0xf bank_mask:0x1
	v_fmac_f32_dpp v149, v87, v193 row_ror:1 row_mask:0xf bank_mask:0x1
	v_fmac_f32_dpp v254, v84, v174 row_ror:2 row_mask:0xf bank_mask:0x1
	v_fmac_f32_dpp v255, v85, v175 row_ror:2 row_mask:0xf bank_mask:0x1
	v_fmac_f32_dpp v148, v86, v176 row_ror:2 row_mask:0xf bank_mask:0x1
	v_fmac_f32_dpp v149, v87, v177 row_ror:2 row_mask:0xf bank_mask:0x1
	v_fma_f32 v246, |v254|, s38, 1.0
	v_fma_f32 v247, |v255|, s38, 1.0
	v_fma_f32 v248, |v148|, s38, 1.0
	v_fma_f32 v249, |v149|, s38, 1.0
	v_pk_mul_f32 v[250:251], v[254:255], v[254:255]
	v_pk_mul_f32 v[252:253], v[148:149], v[148:149]
	v_rcp_f32_e32 v246, v246
	v_rcp_f32_e32 v247, v247
	v_rcp_f32_e32 v248, v248
	v_rcp_f32_e32 v249, v249
	v_pk_mul_f32 v[250:251], v[250:251], s[72:73] op_sel_hi:[1,0]
	v_pk_mul_f32 v[252:253], v[252:253], s[72:73] op_sel_hi:[1,0]
	v_exp_f32_e32 v250, v250
	v_exp_f32_e32 v251, v251
	v_exp_f32_e32 v252, v252
	v_exp_f32_e32 v253, v253
	v_pk_fma_f32 v[238:239], v[246:247], s[56:57], v[218:219] op_sel:[0,0,1] op_sel_hi:[1,0,1]
	v_pk_fma_f32 v[240:241], v[248:249], s[56:57], v[218:219] op_sel:[0,0,1] op_sel_hi:[1,0,1]
	v_pk_fma_f32 v[238:239], v[246:247], v[238:239], s[66:67] op_sel_hi:[1,1,0]
	v_pk_fma_f32 v[240:241], v[248:249], v[240:241], s[66:67] op_sel_hi:[1,1,0]
	v_pk_fma_f32 v[238:239], v[246:247], v[238:239], s[68:69] op_sel_hi:[1,1,0]
	v_pk_fma_f32 v[240:241], v[248:249], v[240:241], s[68:69] op_sel_hi:[1,1,0]
	v_pk_fma_f32 v[238:239], v[246:247], v[238:239], s[70:71] op_sel_hi:[1,1,0]
	v_pk_fma_f32 v[240:241], v[248:249], v[240:241], s[70:71] op_sel_hi:[1,1,0]
	v_pk_mul_f32 v[238:239], v[246:247], v[238:239]
	v_pk_mul_f32 v[240:241], v[248:249], v[240:241]
	v_pk_mul_f32 v[238:239], v[250:251], v[238:239]
	v_pk_mul_f32 v[240:241], v[252:253], v[240:241]
	v_max_f32_e32 v246, 0, v254
	v_max_f32_e32 v247, 0, v255
	v_max_f32_e32 v248, 0, v148
	v_max_f32_e32 v249, 0, v149
	v_fma_f32 v238, -|v254|, v238, v246
	v_fma_f32 v239, -|v255|, v239, v247
	v_fma_f32 v240, -|v148|, v240, v248
	v_fma_f32 v241, -|v149|, v241, v249
	v_pk_fma_f32 v[254:255], v[128:129], v[12:13], v[144:145]
	v_pk_fma_f32 v[148:149], v[130:131], v[14:15], v[146:147]
	v_fmac_f32_dpp v254, v12, v198 row_shr:1 row_mask:0xf bank_mask:0xf
	v_fmac_f32_dpp v255, v13, v199 row_shr:1 row_mask:0xf bank_mask:0xf
	v_fmac_f32_dpp v148, v14, v200 row_shr:1 row_mask:0xf bank_mask:0xf
	v_fmac_f32_dpp v149, v15, v201 row_shr:1 row_mask:0xf bank_mask:0xf
	v_fmac_f32_dpp v254, v12, v182 row_shr:2 row_mask:0xf bank_mask:0xf
	v_fmac_f32_dpp v255, v13, v183 row_shr:2 row_mask:0xf bank_mask:0xf
	v_fmac_f32_dpp v148, v14, v184 row_shr:2 row_mask:0xf bank_mask:0xf
	v_fmac_f32_dpp v149, v15, v185 row_shr:2 row_mask:0xf bank_mask:0xf
	v_fmac_f32_dpp v254, v68, v198 row_ror:1 row_mask:0xf bank_mask:0x1
	v_fmac_f32_dpp v255, v69, v199 row_ror:1 row_mask:0xf bank_mask:0x1
	v_fmac_f32_dpp v148, v70, v200 row_ror:1 row_mask:0xf bank_mask:0x1
	v_fmac_f32_dpp v149, v71, v201 row_ror:1 row_mask:0xf bank_mask:0x1
	v_fmac_f32_dpp v254, v68, v182 row_ror:2 row_mask:0xf bank_mask:0x1
	v_fmac_f32_dpp v255, v69, v183 row_ror:2 row_mask:0xf bank_mask:0x1
	v_fmac_f32_dpp v148, v70, v184 row_ror:2 row_mask:0xf bank_mask:0x1
	v_fmac_f32_dpp v149, v71, v185 row_ror:2 row_mask:0xf bank_mask:0x1
	v_pk_mul_f32 v[254:255], v[238:239], v[254:255]
	v_pk_mul_f32 v[148:149], v[240:241], v[148:149]
	v_cvt_pk_bf16_f32 v244, v254, v255
	v_cvt_pk_bf16_f32 v245, v148, v149
	s_add_u32 s56, s46, 0xb0000
	s_addc_u32 s57, s47, 0
	global_store_dwordx4 v151, v[242:245], s[56:57]
	s_and_b32 s14, s88, 7
	s_cmp_eq_u32 s14, 7
	s_cselect_b32 s14, s73, 0
	s_cmp_eq_u32 s14, 1
	s_cbranch_scc0 .Lfe_done
	s_lshr_b32 s14, s88, 3
	s_mul_i32 s14, s14, 0xb000
	v_mul_i32_i24_e32 v246, 0x5800, v216
	v_add_u32_e32 v246, s14, v246
	v_add_u32_e32 v246, v246, v237
	v_add_u32_e32 v247, 0x2c00, v246
	s_mov_b64 s[14:15], exec
	s_mov_b64 exec, s[10:11]
	global_store_dwordx4 v246, v[56:59], s[50:51]
	global_store_dwordx4 v246, v[24:27], s[50:51] offset:16
	global_store_dwordx4 v247, v[40:43], s[50:51]
	global_store_dwordx4 v247, v[8:11], s[50:51] offset:16
	s_mov_b64 exec, s[14:15]
